# prep_unit: defer BD-load wait in wave 0, scalar-load dt_bias/a_log at unit start
# baseline (speedup 1.0000x reference)
.LBB0_271:
	s_or_b64 exec, exec, s[0:1]
	v_readlane_b32 s0, v254, 22
	s_waitcnt lgkmcnt(0)
	s_barrier
	s_nop 0
	v_mov_b32_e32 v0, s0
	ds_read_b32 v0, v0
	s_movk_i32 s0, 0xff
	s_waitcnt lgkmcnt(0)
	v_cmp_lt_u32_e32 vcc, s0, v0
	s_mov_b64 s[0:1], -1
	s_cbranch_vccnz .LBB0_266
	v_lshl_add_u32 v0, v0, 1, v147
	v_ashrrev_i32_e32 v2, 31, v0
	v_lshrrev_b32_e32 v2, 30, v2
	v_add_u32_e32 v2, v0, v2
	v_ashrrev_i32_e32 v162, 2, v2
	v_and_b32_e32 v2, -4, v2
	v_sub_u32_e32 v161, v0, v2
	v_and_b32_e32 v164, 1, v162
	v_lshlrev_b32_e32 v2, 4, v162
	v_sub_u32_e32 v0, 3, v161
	v_cmp_eq_u32_e64 s[44:45], 0, v164
	v_and_b32_e32 v2, 0xffffff00, v2
	v_mov_b32_e32 v148, v156
	v_cndmask_b32_e64 v0, v0, v161, s[44:45]
	v_add_u32_e32 v26, 0x8000, v2
	v_bfe_u32 v163, v162, 1, 3
	v_ashrrev_i32_e32 v27, 31, v26
	v_lshlrev_b32_e32 v4, 6, v0
	v_cmp_gt_u32_e64 s[46:47], 64, v148
	v_bfrev_b32_e32 v165, 1
	v_lshl_or_b32 v130, v164, 3, v163
	v_lshlrev_b32_e32 v130, 2, v130
	s_nop 0
	v_readfirstlane_b32 s100, v130
	s_nop 4
	s_load_dword s101, s[82:83], s100
	s_load_dword s100, s[80:81], s100
	v_mov_b32_e32 v130, 0
	v_mov_b32_e32 v166, 0
	s_and_saveexec_b64 s[0:1], s[46:47]
	s_cbranch_execz .LBB0_274
	v_xor_b32_e32 v0, 63, v148
	v_ashrrev_i32_e32 v5, 31, v4
	v_cndmask_b32_e64 v0, v0, v148, s[44:45]
	v_lshl_add_u64 v[2:3], v[4:5], 0, v[26:27]
	v_or_b32_e32 v2, v2, v0
	v_readlane_b32 s22, v251, 58
	v_lshlrev_b64 v[2:3], 7, v[2:3]
	v_readlane_b32 s23, v251, 59
	v_lshlrev_b32_e32 v0, 5, v164
	s_nop 0
	v_lshl_add_u64 v[2:3], s[22:23], 0, v[2:3]
	v_lshl_add_u64 v[2:3], v[2:3], 0, v[0:1]
	v_lshlrev_b32_e32 v0, 2, v163
	v_lshl_add_u64 v[2:3], v[2:3], 0, v[0:1]
	global_load_dword v165, v[2:3], off
	global_load_dword v166, v[2:3], off offset:64

.LBB0_310:
	s_or_b64 exec, exec, s[0:1]
	v_lshlrev_b32_e32 v0, 2, v30
	v_lshl_add_u64 v[34:35], s[78:79], 0, v[0:1]
	s_movk_i32 s0, 0x3000
	v_add_co_u32_e32 v32, vcc, s0, v34
	s_mov_b64 s[0:1], 0x6000
	global_load_dwordx4 v[26:29], v0, s[78:79] offset:16
	global_load_dwordx4 v[38:41], v0, s[78:79]
	v_addc_co_u32_e32 v33, vcc, 0, v35, vcc
	v_lshl_add_u64 v[36:37], v[34:35], 0, s[0:1]
	s_movk_i32 s0, 0x6000
	v_sub_u32_e32 v0, 60, v168
	v_lshl_add_u64 v[30:31], v[34:35], 0, s[24:25]
	v_add_co_u32_e32 v34, vcc, s0, v34
	v_cndmask_b32_e64 v0, v0, v168, s[44:45]
	v_and_b32_e32 v150, 56, v150
	s_mov_b32 s0, 0x7ffffff8
	v_bitop3_b32 v150, v0, v150, s0 bitop3:0x6c
	s_waitcnt vmcnt(14)
	v_lshlrev_b32_e32 v154, 16, v145
	v_and_b32_e32 v155, 0xffff0000, v145
	v_and_or_b32 v169, v0, 4, v150
	v_lshlrev_b32_e32 v150, 16, v133
	v_and_b32_e32 v151, 0xffff0000, v133
	s_waitcnt vmcnt(10)
	v_pk_mul_f32 v[152:153], v[124:125], v[154:155]
	v_lshlrev_b32_e32 v172, 16, v132
	v_pk_fma_f32 v[152:153], v[120:121], v[150:151], v[152:153]
	v_lshlrev_b32_e32 v150, 16, v141
	v_and_b32_e32 v151, 0xffff0000, v141
	s_waitcnt vmcnt(8)
	v_pk_fma_f32 v[152:153], v[128:129], v[150:151], v[152:153]
	v_and_b32_e32 v173, 0xffff0000, v132
	v_mul_f32_e32 v0, 0xbfb8aa3b, v152
	v_exp_f32_e32 v133, v0
	v_mul_f32_e32 v0, 0xbfb8aa3b, v153
	v_exp_f32_e32 v141, v0
	v_lshlrev_b32_e32 v132, 16, v144
	v_add_f32_e32 v133, 1.0, v133
	v_rcp_f32_e32 v170, v133
	v_add_f32_e32 v133, 1.0, v141
	v_rcp_f32_e32 v171, v133
	v_and_b32_e32 v133, 0xffff0000, v144
	v_lshlrev_b32_e32 v144, 16, v140
	v_and_b32_e32 v145, 0xffff0000, v140
	v_pk_mul_f32 v[140:141], v[122:123], v[132:133]
	v_lshlrev_b32_e32 v176, 16, v143
	v_pk_fma_f32 v[140:141], v[118:119], v[172:173], v[140:141]
	v_and_b32_e32 v177, 0xffff0000, v143
	v_pk_fma_f32 v[172:173], v[126:127], v[144:145], v[140:141]
	v_lshlrev_b32_e32 v174, 16, v131
	v_mul_f32_e32 v140, 0xbfb8aa3b, v172
	v_exp_f32_e32 v140, v140
	v_mul_f32_e32 v141, 0xbfb8aa3b, v173
	v_exp_f32_e32 v141, v141
	v_and_b32_e32 v175, 0xffff0000, v131
	v_add_f32_e32 v140, 1.0, v140
	v_pk_mul_f32 v[178:179], v[112:113], v[176:177]
	v_pk_mul_f32 v[170:171], v[152:153], v[170:171]
	v_rcp_f32_e32 v152, v140
	v_add_f32_e32 v153, 1.0, v141
	v_lshlrev_b32_e32 v140, 16, v139
	v_and_b32_e32 v141, 0xffff0000, v139
	v_pk_fma_f32 v[174:175], v[104:105], v[174:175], v[178:179]
	v_rcp_f32_e32 v153, v153
	v_pk_fma_f32 v[174:175], v[116:117], v[140:141], v[174:175]
	v_pk_mul_f32 v[184:185], v[124:125], v[150:151]
	v_mul_f32_e32 v131, 0xbfb8aa3b, v174
	v_exp_f32_e32 v131, v131
	v_mul_f32_e32 v139, 0xbfb8aa3b, v175
	v_exp_f32_e32 v139, v139
	v_pk_mul_f32 v[172:173], v[172:173], v[152:153]
	v_add_f32_e32 v131, 1.0, v131
	v_rcp_f32_e32 v178, v131
	v_add_f32_e32 v131, 1.0, v139
	v_rcp_f32_e32 v179, v131
	v_and_b32_e32 v131, 0xffff0000, v142
	v_lshlrev_b32_e32 v152, 16, v138
	v_and_b32_e32 v153, 0xffff0000, v138
	v_pk_mul_f32 v[174:175], v[174:175], v[178:179]
	v_lshlrev_b32_e32 v178, 16, v130
	v_and_b32_e32 v179, 0xffff0000, v130
	v_lshlrev_b32_e32 v130, 16, v142
	v_pk_mul_f32 v[138:139], v[110:111], v[130:131]
	v_pk_fma_f32 v[184:185], v[120:121], v[154:155], v[184:185]
	v_pk_fma_f32 v[138:139], v[102:103], v[178:179], v[138:139]
	v_lshlrev_b32_e32 v154, 16, v137
	v_pk_fma_f32 v[138:139], v[114:115], v[152:153], v[138:139]
	v_and_b32_e32 v155, 0xffff0000, v137
	v_mul_f32_e32 v142, 0xbfb8aa3b, v138
	v_mul_f32_e32 v143, 0xbfb8aa3b, v139
	v_exp_f32_e32 v142, v142
	v_exp_f32_e32 v143, v143
	v_pk_fma_f32 v[184:185], v[128:129], v[154:155], v[184:185]
	v_pk_mul_f32 v[192:193], v[112:113], v[140:141]
	v_mul_f32_e32 v137, 0xbfb8aa3b, v184
	v_exp_f32_e32 v137, v137
	v_mul_f32_e32 v186, 0xbfb8aa3b, v185
	v_add_f32_e32 v142, 1.0, v142
	v_add_f32_e32 v143, 1.0, v143
	v_exp_f32_e32 v187, v186
	v_rcp_f32_e32 v142, v142
	v_rcp_f32_e32 v143, v143
	v_add_f32_e32 v137, 1.0, v137
	v_rcp_f32_e32 v186, v137
	v_add_f32_e32 v137, 1.0, v187
	v_rcp_f32_e32 v187, v137
	v_pk_mul_f32 v[188:189], v[138:139], v[142:143]
	v_lshlrev_b32_e32 v142, 16, v136
	v_and_b32_e32 v143, 0xffff0000, v136
	v_pk_mul_f32 v[136:137], v[122:123], v[144:145]
	v_lshlrev_b32_e32 v138, 16, v135
	v_pk_fma_f32 v[132:133], v[118:119], v[132:133], v[136:137]
	v_and_b32_e32 v139, 0xffff0000, v135
	v_pk_fma_f32 v[132:133], v[126:127], v[142:143], v[132:133]
	v_pk_fma_f32 v[176:177], v[104:105], v[176:177], v[192:193]
	v_mul_f32_e32 v136, 0xbfb8aa3b, v132
	v_mul_f32_e32 v137, 0xbfb8aa3b, v133
	v_exp_f32_e32 v136, v136
	v_exp_f32_e32 v137, v137
	v_pk_fma_f32 v[176:177], v[116:117], v[138:139], v[176:177]
	v_pk_mul_f32 v[190:191], v[188:189], v[188:189]
	v_add_f32_e32 v136, 1.0, v136
	v_add_f32_e32 v137, 1.0, v137
	v_mul_f32_e32 v135, 0xbfb8aa3b, v176
	v_rcp_f32_e32 v136, v136
	v_rcp_f32_e32 v137, v137
	v_exp_f32_e32 v135, v135
	v_mul_f32_e32 v192, 0xbfb8aa3b, v177
	v_exp_f32_e32 v206, v192
	v_pk_mul_f32 v[192:193], v[132:133], v[136:137]
	v_add_f32_e32 v132, 1.0, v135
	v_lshlrev_b32_e32 v136, 16, v134
	v_and_b32_e32 v137, 0xffff0000, v134
	v_pk_mul_f32 v[134:135], v[110:111], v[152:153]
	v_add_f32_e32 v133, 1.0, v206
	v_pk_fma_f32 v[130:131], v[102:103], v[130:131], v[134:135]
	v_rcp_f32_e32 v132, v132
	v_pk_fma_f32 v[130:131], v[114:115], v[136:137], v[130:131]
	v_rcp_f32_e32 v133, v133
	v_mul_f32_e32 v134, 0xbfb8aa3b, v130
	v_mul_f32_e32 v135, 0xbfb8aa3b, v131
	v_exp_f32_e32 v134, v134
	v_exp_f32_e32 v135, v135
	v_pk_mul_f32 v[176:177], v[176:177], v[132:133]
	v_pk_mul_f32 v[178:179], v[174:175], v[174:175]
	v_add_f32_e32 v134, 1.0, v134
	v_add_f32_e32 v135, 1.0, v135
	v_rcp_f32_e32 v134, v134
	v_rcp_f32_e32 v135, v135
	v_pk_mul_f32 v[132:133], v[176:177], v[176:177]
	v_mov_b32_e32 v209, v190
	v_pk_mul_f32 v[182:183], v[172:173], v[172:173]
	v_pk_mul_f32 v[130:131], v[130:131], v[134:135]
	v_pk_mul_f32 v[206:207], v[192:193], v[192:193]
	v_pk_mul_f32 v[134:135], v[130:131], v[130:131]
	v_pk_mul_f32 v[184:185], v[184:185], v[186:187]
	v_mov_b32_e32 v208, v134
	v_mov_b32_e32 v190, v135
	v_pk_add_f32 v[134:135], v[208:209], v[190:191]
	v_mov_b32_e32 v190, v132
	v_mov_b32_e32 v191, v178
	v_pk_add_f32 v[134:135], v[190:191], v[134:135]
	v_mov_b32_e32 v178, v133
	v_pk_add_f32 v[132:133], v[178:179], v[134:135]
	v_mov_b32_e32 v134, v206
	v_mov_b32_e32 v135, v182
	v_pk_mul_f32 v[180:181], v[170:171], v[170:171]
	v_pk_mul_f32 v[186:187], v[184:185], v[184:185]
	v_pk_add_f32 v[132:133], v[134:135], v[132:133]
	v_mov_b32_e32 v182, v207
	v_pk_add_f32 v[132:133], v[182:183], v[132:133]
	v_mov_b32_e32 v134, v186
	v_mov_b32_e32 v135, v180
	v_pk_add_f32 v[132:133], v[134:135], v[132:133]
	v_mov_b32_e32 v180, v187
	v_pk_add_f32 v[132:133], v[180:181], v[132:133]
	s_mov_b32 s2, 0x358637bd
	v_addc_co_u32_e32 v35, vcc, 0, v35, vcc
	v_mov_b32_dpp v135, v133 quad_perm:[1,0,3,2] row_mask:0xf bank_mask:0xf bound_ctrl:1
	v_mov_b32_dpp v134, v132 quad_perm:[1,0,3,2] row_mask:0xf bank_mask:0xf bound_ctrl:1
	v_pk_add_f32 v[132:133], v[132:133], v[134:135]
	v_sub_u32_e32 v203, 63, v168
	v_lshl_add_u32 v0, v167, 1, v146
	v_mov_b32_dpp v135, v133 quad_perm:[2,3,0,1] row_mask:0xf bank_mask:0xf bound_ctrl:1
	v_mov_b32_dpp v134, v132 quad_perm:[2,3,0,1] row_mask:0xf bank_mask:0xf bound_ctrl:1
	v_pk_add_f32 v[132:133], v[132:133], v[134:135]
	global_load_dwordx4 v[42:45], v[32:33], off
	s_nop 0
	global_load_dwordx4 v[30:33], v[30:31], off offset:16
	v_mov_b32_dpp v135, v133 row_half_mirror row_mask:0xf bank_mask:0xf bound_ctrl:1
	v_mov_b32_dpp v134, v132 row_half_mirror row_mask:0xf bank_mask:0xf bound_ctrl:1
	v_pk_add_f32 v[132:133], v[132:133], v[134:135]
	global_load_dwordx4 v[46:49], v[34:35], off
	s_nop 0
	global_load_dwordx4 v[34:37], v[36:37], off offset:16
	v_mov_b32_dpp v135, v133 row_mirror row_mask:0xf bank_mask:0xf bound_ctrl:1
	v_mov_b32_dpp v134, v132 row_mirror row_mask:0xf bank_mask:0xf bound_ctrl:1
	v_pk_add_f32 v[132:133], v[132:133], v[134:135]
	v_and_b32_e32 v160, 63, v148
	v_pk_add_f32 v[134:135], v[132:133], s[2:3] op_sel_hi:[1,0]
	s_nop 0
	v_mul_f32_e32 v132, 0x4b800000, v135
	v_cmp_gt_f32_e32 vcc, s72, v135
	s_nop 1
	v_cndmask_b32_e32 v132, v135, v132, vcc
	v_rsq_f32_e32 v135, v132
	v_cndmask_b32_e64 v132, v203, v168, s[44:45]
	v_mad_u64_u32 v[132:133], s[0:1], v132, s14, v[0:1]
	v_mul_f32_e32 v133, 0x45800000, v135
	v_cndmask_b32_e32 v178, v135, v133, vcc
	v_mul_f32_e32 v133, 0x4b800000, v134
	v_cmp_gt_f32_e32 vcc, s72, v134
	v_pk_mul_f32 v[180:181], v[188:189], v[178:179] op_sel_hi:[1,0]
	v_pk_mul_f32 v[174:175], v[174:175], v[178:179] op_sel_hi:[1,0]
	v_cndmask_b32_e32 v133, v134, v133, vcc
	v_rsq_f32_e32 v133, v133
	v_pk_mul_f32 v[172:173], v[172:173], v[178:179] op_sel_hi:[1,0]
	v_pk_mul_f32 v[178:179], v[170:171], v[178:179] op_sel_hi:[1,0]
	v_cvt_pk_bf16_f32 v170, v180, v181
	v_mul_f32_e32 v134, 0x45800000, v133
	v_cvt_pk_bf16_f32 v171, v174, v175
	v_cvt_pk_bf16_f32 v172, v172, v173
	v_cvt_pk_bf16_f32 v173, v178, v179
	v_cndmask_b32_e32 v134, v133, v134, vcc
	ds_write_b128 v132, v[170:173]
	v_pk_mul_f32 v[130:131], v[130:131], v[134:135] op_sel_hi:[1,0]
	v_pk_mul_f32 v[172:173], v[176:177], v[134:135] op_sel_hi:[1,0]
	v_pk_mul_f32 v[174:175], v[192:193], v[134:135] op_sel_hi:[1,0]
	v_pk_mul_f32 v[134:135], v[184:185], v[134:135] op_sel_hi:[1,0]
	v_or_b32_e32 v133, 1, v168
	v_cvt_pk_bf16_f32 v171, v172, v173
	v_cvt_pk_bf16_f32 v173, v134, v135
	v_pk_mul_f32 v[134:135], v[124:125], v[154:155]
	v_sub_u32_e32 v170, 63, v133
	v_pk_fma_f32 v[134:135], v[120:121], v[150:151], v[134:135]
	v_lshlrev_b32_e32 v150, 16, v109
	v_and_b32_e32 v151, 0xffff0000, v109
	v_cndmask_b32_e64 v133, v170, v133, s[44:45]
	v_pk_fma_f32 v[134:135], v[128:129], v[150:151], v[134:135]
	v_pk_mul_f32 v[124:125], v[124:125], v[150:151]
	v_cvt_pk_bf16_f32 v170, v130, v131
	v_mad_u64_u32 v[130:131], s[0:1], v133, s14, v[0:1]
	v_mul_f32_e32 v109, 0xbfb8aa3b, v134
	v_pk_fma_f32 v[120:121], v[120:121], v[154:155], v[124:125]
	v_lshlrev_b32_e32 v124, 16, v101
	v_and_b32_e32 v125, 0xffff0000, v101
	v_exp_f32_e32 v109, v109
	v_mul_f32_e32 v131, 0xbfb8aa3b, v135
	v_pk_fma_f32 v[120:121], v[128:129], v[124:125], v[120:121]
	v_exp_f32_e32 v131, v131
	v_mul_f32_e32 v101, 0xbfb8aa3b, v120
	v_exp_f32_e32 v101, v101
	v_mul_f32_e32 v124, 0xbfb8aa3b, v121
	v_exp_f32_e32 v125, v124
	v_cvt_pk_bf16_f32 v172, v174, v175
	v_add_f32_e32 v109, 1.0, v109
	ds_write_b128 v130, v[170:173]
	v_rcp_f32_e32 v170, v109
	v_add_f32_e32 v109, 1.0, v131
	v_rcp_f32_e32 v171, v109
	v_lshlrev_b32_e32 v172, 16, v108
	v_and_b32_e32 v173, 0xffff0000, v108
	v_pk_mul_f32 v[108:109], v[122:123], v[142:143]
	v_add_f32_e32 v101, 1.0, v101
	v_pk_fma_f32 v[108:109], v[118:119], v[144:145], v[108:109]
	v_rcp_f32_e32 v124, v101
	v_add_f32_e32 v101, 1.0, v125
	v_pk_fma_f32 v[108:109], v[126:127], v[172:173], v[108:109]
	v_rcp_f32_e32 v125, v101
	v_mul_f32_e32 v131, 0xbfb8aa3b, v108
	v_exp_f32_e32 v131, v131
	v_mul_f32_e32 v133, 0xbfb8aa3b, v109
	v_exp_f32_e32 v133, v133
	v_pk_mul_f32 v[174:175], v[112:113], v[138:139]
	v_pk_mul_f32 v[134:135], v[134:135], v[170:171]
	v_lshlrev_b32_e32 v170, 16, v107
	v_and_b32_e32 v171, 0xffff0000, v107
	v_pk_fma_f32 v[140:141], v[104:105], v[140:141], v[174:175]
	v_pk_mul_f32 v[120:121], v[120:121], v[124:125]
	v_lshlrev_b32_e32 v124, 16, v100
	v_and_b32_e32 v125, 0xffff0000, v100
	v_pk_mul_f32 v[100:101], v[122:123], v[172:173]
	v_pk_fma_f32 v[140:141], v[116:117], v[170:171], v[140:141]
	v_pk_fma_f32 v[100:101], v[118:119], v[142:143], v[100:101]
	v_add_f32_e32 v131, 1.0, v131
	v_mul_f32_e32 v107, 0xbfb8aa3b, v140
	v_pk_fma_f32 v[100:101], v[126:127], v[124:125], v[100:101]
	v_rcp_f32_e32 v144, v131
	v_add_f32_e32 v131, 1.0, v133
	v_exp_f32_e32 v107, v107
	v_mul_f32_e32 v133, 0xbfb8aa3b, v141
	v_mul_f32_e32 v118, 0xbfb8aa3b, v100
	v_exp_f32_e32 v133, v133
	v_exp_f32_e32 v122, v118
	v_mul_f32_e32 v118, 0xbfb8aa3b, v101
	v_exp_f32_e32 v123, v118
	v_pk_mul_f32 v[112:113], v[112:113], v[170:171]
	v_lshlrev_b32_e32 v124, 16, v99
	v_and_b32_e32 v125, 0xffff0000, v99
	v_pk_fma_f32 v[104:105], v[104:105], v[138:139], v[112:113]
	v_add_f32_e32 v107, 1.0, v107
	v_pk_fma_f32 v[104:105], v[116:117], v[124:125], v[104:105]
	v_rcp_f32_e32 v174, v107
	v_add_f32_e32 v107, 1.0, v133
	v_mul_f32_e32 v99, 0xbfb8aa3b, v104
	v_rcp_f32_e32 v175, v107
	v_add_f32_e32 v122, 1.0, v122
	v_add_f32_e32 v123, 1.0, v123
	v_exp_f32_e32 v99, v99
	v_mul_f32_e32 v112, 0xbfb8aa3b, v105
	v_rcp_f32_e32 v122, v122
	v_rcp_f32_e32 v123, v123
	v_exp_f32_e32 v116, v112
	v_pk_mul_f32 v[140:141], v[140:141], v[174:175]
	v_lshlrev_b32_e32 v174, 16, v106
	v_and_b32_e32 v175, 0xffff0000, v106
	v_pk_mul_f32 v[106:107], v[110:111], v[136:137]
	v_add_f32_e32 v99, 1.0, v99
	v_pk_fma_f32 v[106:107], v[102:103], v[152:153], v[106:107]
	v_pk_mul_f32 v[112:113], v[100:101], v[122:123]
	v_rcp_f32_e32 v100, v99
	v_add_f32_e32 v101, 1.0, v116
	v_lshlrev_b32_e32 v116, 16, v98
	v_and_b32_e32 v117, 0xffff0000, v98
	v_pk_mul_f32 v[98:99], v[110:111], v[174:175]
	v_pk_fma_f32 v[106:107], v[114:115], v[174:175], v[106:107]
	v_pk_fma_f32 v[98:99], v[102:103], v[136:137], v[98:99]
	v_rcp_f32_e32 v145, v131
	v_mul_f32_e32 v131, 0xbfb8aa3b, v106
	v_pk_fma_f32 v[98:99], v[114:115], v[116:117], v[98:99]
	v_exp_f32_e32 v131, v131
	v_mul_f32_e32 v133, 0xbfb8aa3b, v107
	v_mul_f32_e32 v102, 0xbfb8aa3b, v98
	v_mul_f32_e32 v103, 0xbfb8aa3b, v99
	v_exp_f32_e32 v133, v133
	v_exp_f32_e32 v102, v102
	v_exp_f32_e32 v103, v103
	v_add_f32_e32 v131, 1.0, v131
	v_rcp_f32_e32 v178, v131
	v_add_f32_e32 v131, 1.0, v133
	v_add_f32_e32 v102, 1.0, v102
	v_add_f32_e32 v103, 1.0, v103
	v_rcp_f32_e32 v179, v131
	v_rcp_f32_e32 v102, v102
	v_rcp_f32_e32 v103, v103
	v_rcp_f32_e32 v101, v101
	v_pk_mul_f32 v[106:107], v[106:107], v[178:179]
	v_pk_mul_f32 v[152:153], v[140:141], v[140:141]
	v_pk_mul_f32 v[114:115], v[98:99], v[102:103]
	v_pk_mul_f32 v[128:129], v[106:107], v[106:107]
	v_pk_mul_f32 v[104:105], v[104:105], v[100:101]
	v_pk_mul_f32 v[98:99], v[114:115], v[114:115]
	v_pk_mul_f32 v[100:101], v[104:105], v[104:105]
	v_mov_b32_e32 v102, v98
	v_mov_b32_e32 v103, v128
	v_mov_b32_e32 v128, v99
	v_pk_mul_f32 v[108:109], v[108:109], v[144:145]
	v_pk_add_f32 v[98:99], v[102:103], v[128:129]
	v_mov_b32_e32 v102, v100
	v_mov_b32_e32 v103, v152
	v_pk_mul_f32 v[144:145], v[108:109], v[108:109]
	v_pk_mul_f32 v[110:111], v[112:113], v[112:113]
	v_pk_add_f32 v[98:99], v[102:103], v[98:99]
	v_mov_b32_e32 v152, v101
	v_pk_add_f32 v[98:99], v[152:153], v[98:99]
	v_mov_b32_e32 v100, v110
	v_mov_b32_e32 v101, v144
	v_pk_mul_f32 v[176:177], v[134:135], v[134:135]
	v_pk_mul_f32 v[118:119], v[120:121], v[120:121]
	v_pk_add_f32 v[98:99], v[100:101], v[98:99]
	v_mov_b32_e32 v144, v111
	v_pk_add_f32 v[98:99], v[144:145], v[98:99]
	v_mov_b32_e32 v100, v118
	v_mov_b32_e32 v101, v176
	v_pk_add_f32 v[98:99], v[100:101], v[98:99]
	v_mov_b32_e32 v176, v119
	v_pk_add_f32 v[98:99], v[176:177], v[98:99]
	v_or_b32_e32 v131, 2, v168
	v_sub_u32_e32 v133, 63, v131
	v_mov_b32_dpp v101, v99 quad_perm:[1,0,3,2] row_mask:0xf bank_mask:0xf bound_ctrl:1
	v_mov_b32_dpp v100, v98 quad_perm:[1,0,3,2] row_mask:0xf bank_mask:0xf bound_ctrl:1
	v_pk_add_f32 v[98:99], v[98:99], v[100:101]
	v_lshlrev_b32_e32 v118, 16, v89
	v_and_b32_e32 v119, 0xffff0000, v89
	v_mov_b32_dpp v101, v99 quad_perm:[2,3,0,1] row_mask:0xf bank_mask:0xf bound_ctrl:1
	v_mov_b32_dpp v100, v98 quad_perm:[2,3,0,1] row_mask:0xf bank_mask:0xf bound_ctrl:1
	v_pk_add_f32 v[98:99], v[98:99], v[100:101]
	s_nop 1
	v_mov_b32_dpp v101, v99 row_half_mirror row_mask:0xf bank_mask:0xf bound_ctrl:1
	v_mov_b32_dpp v100, v98 row_half_mirror row_mask:0xf bank_mask:0xf bound_ctrl:1
	v_pk_add_f32 v[98:99], v[98:99], v[100:101]
	s_nop 1
	v_mov_b32_dpp v101, v99 row_mirror row_mask:0xf bank_mask:0xf bound_ctrl:1
	v_mov_b32_dpp v100, v98 row_mirror row_mask:0xf bank_mask:0xf bound_ctrl:1
	v_pk_add_f32 v[98:99], v[98:99], v[100:101]
	s_nop 0
	v_pk_add_f32 v[100:101], v[98:99], s[2:3] op_sel_hi:[1,0]
	v_cndmask_b32_e64 v99, v133, v131, s[44:45]
	v_mul_f32_e32 v98, 0x4b800000, v101
	v_cmp_gt_f32_e32 vcc, s72, v101
	v_mad_u64_u32 v[102:103], s[0:1], v99, s14, v[0:1]
	s_nop 0
	v_cndmask_b32_e32 v98, v101, v98, vcc
	v_rsq_f32_e32 v98, v98
	v_mul_f32_e32 v101, 0x4b800000, v100
	v_and_b32_e32 v133, 0xffff0000, v54
	v_mul_f32_e32 v99, 0x45800000, v98
	v_cndmask_b32_e32 v98, v98, v99, vcc
	v_cmp_gt_f32_e32 vcc, s72, v100
	v_pk_mul_f32 v[106:107], v[106:107], v[98:99] op_sel_hi:[1,0]
	v_pk_mul_f32 v[110:111], v[140:141], v[98:99] op_sel_hi:[1,0]
	v_cndmask_b32_e32 v100, v100, v101, vcc
	v_rsq_f32_e32 v103, v100
	v_pk_mul_f32 v[108:109], v[108:109], v[98:99] op_sel_hi:[1,0]
	v_pk_mul_f32 v[116:117], v[134:135], v[98:99] op_sel_hi:[1,0]
	v_cvt_pk_bf16_f32 v98, v106, v107
	v_cvt_pk_bf16_f32 v99, v110, v111
	v_cvt_pk_bf16_f32 v100, v108, v109
	v_cvt_pk_bf16_f32 v101, v116, v117
	ds_write_b128 v102, v[98:101]
	v_mul_f32_e32 v98, 0x45800000, v103
	v_cndmask_b32_e32 v98, v103, v98, vcc
	v_pk_mul_f32 v[100:101], v[114:115], v[98:99] op_sel_hi:[1,0]
	v_pk_mul_f32 v[104:105], v[104:105], v[98:99] op_sel_hi:[1,0]
	v_pk_mul_f32 v[106:107], v[112:113], v[98:99] op_sel_hi:[1,0]
	v_pk_mul_f32 v[108:109], v[120:121], v[98:99] op_sel_hi:[1,0]
	v_or_b32_e32 v98, 3, v168
	v_sub_u32_e32 v99, 63, v98
	v_lshlrev_b32_e32 v110, 16, v97
	v_and_b32_e32 v111, 0xffff0000, v97
	v_cndmask_b32_e64 v103, v99, v98, s[44:45]
	v_cvt_pk_bf16_f32 v98, v100, v101
	v_cvt_pk_bf16_f32 v99, v104, v105
	v_lshlrev_b32_e32 v100, 16, v85
	v_and_b32_e32 v101, 0xffff0000, v85
	s_waitcnt vmcnt(8)
	v_pk_mul_f32 v[104:105], v[76:77], v[110:111]
	v_lshlrev_b32_e32 v116, 16, v84
	v_pk_fma_f32 v[100:101], v[72:73], v[100:101], v[104:105]
	v_lshlrev_b32_e32 v104, 16, v93
	v_and_b32_e32 v105, 0xffff0000, v93
	s_waitcnt vmcnt(6)
	v_pk_fma_f32 v[112:113], v[80:81], v[104:105], v[100:101]
	v_and_b32_e32 v117, 0xffff0000, v84
	v_mul_f32_e32 v85, 0xbfb8aa3b, v112
	v_exp_f32_e32 v85, v85
	v_mul_f32_e32 v93, 0xbfb8aa3b, v113
	v_exp_f32_e32 v93, v93
	v_lshlrev_b32_e32 v84, 16, v96
	v_add_f32_e32 v85, 1.0, v85
	v_rcp_f32_e32 v114, v85
	v_and_b32_e32 v85, 0xffff0000, v96
	v_cvt_pk_bf16_f32 v100, v106, v107
	v_add_f32_e32 v97, 1.0, v93
	v_lshlrev_b32_e32 v106, 16, v92
	v_and_b32_e32 v107, 0xffff0000, v92
	v_pk_mul_f32 v[92:93], v[74:75], v[84:85]
	v_rcp_f32_e32 v115, v97
	v_pk_fma_f32 v[92:93], v[70:71], v[116:117], v[92:93]
	v_lshlrev_b32_e32 v116, 16, v90
	v_pk_fma_f32 v[92:93], v[78:79], v[106:107], v[92:93]
	v_pk_mul_f32 v[120:121], v[112:113], v[114:115]
	v_mul_f32_e32 v96, 0xbfb8aa3b, v92
	v_mul_f32_e32 v101, 0xbfb8aa3b, v93
	v_exp_f32_e32 v96, v96
	v_exp_f32_e32 v101, v101
	v_lshlrev_b32_e32 v114, 16, v82
	v_and_b32_e32 v115, 0xffff0000, v82
	v_add_f32_e32 v96, 1.0, v96
	v_add_f32_e32 v97, 1.0, v101
	v_rcp_f32_e32 v96, v96
	v_rcp_f32_e32 v97, v97
	v_cvt_pk_bf16_f32 v101, v108, v109
	v_lshlrev_b32_e32 v108, 16, v91
	v_and_b32_e32 v109, 0xffff0000, v91
	v_pk_mul_f32 v[124:125], v[92:93], v[96:97]
	v_lshlrev_b32_e32 v96, 16, v95
	v_and_b32_e32 v97, 0xffff0000, v95
	v_lshlrev_b32_e32 v92, 16, v83
	v_and_b32_e32 v93, 0xffff0000, v83
	v_pk_mul_f32 v[112:113], v[64:65], v[96:97]
	v_lshlrev_b32_e32 v82, 16, v94
	v_pk_fma_f32 v[92:93], v[60:61], v[92:93], v[112:113]
	v_and_b32_e32 v117, 0xffff0000, v90
	v_pk_fma_f32 v[92:93], v[68:69], v[108:109], v[92:93]
	v_pk_mul_f32 v[136:137], v[64:65], v[108:109]
	v_mul_f32_e32 v83, 0xbfb8aa3b, v92
	v_exp_f32_e32 v83, v83
	v_mul_f32_e32 v91, 0xbfb8aa3b, v93
	v_exp_f32_e32 v91, v91
	v_pk_fma_f32 v[96:97], v[60:61], v[96:97], v[136:137]
	v_add_f32_e32 v83, 1.0, v83
	v_rcp_f32_e32 v112, v83
	v_add_f32_e32 v83, 1.0, v91
	v_rcp_f32_e32 v113, v83
	v_and_b32_e32 v83, 0xffff0000, v94
	v_pk_mul_f32 v[90:91], v[62:63], v[82:83]
	v_pk_mul_f32 v[126:127], v[124:125], v[124:125]
	v_pk_fma_f32 v[90:91], v[58:59], v[114:115], v[90:91]
	v_pk_mul_f32 v[122:123], v[120:121], v[120:121]
	v_pk_fma_f32 v[90:91], v[66:67], v[116:117], v[90:91]
	s_nop 0
	v_mul_f32_e32 v94, 0xbfb8aa3b, v90
	v_exp_f32_e32 v114, v94
	v_mul_f32_e32 v94, 0xbfb8aa3b, v91
	v_exp_f32_e32 v115, v94
	v_pk_mul_f32 v[94:95], v[92:93], v[112:113]
	v_pk_mul_f32 v[112:113], v[76:77], v[104:105]
	v_add_f32_e32 v92, 1.0, v114
	v_pk_fma_f32 v[110:111], v[72:73], v[110:111], v[112:113]
	v_add_f32_e32 v93, 1.0, v115
	v_pk_fma_f32 v[110:111], v[80:81], v[118:119], v[110:111]
	v_lshlrev_b32_e32 v114, 16, v88
	v_mul_f32_e32 v89, 0xbfb8aa3b, v110
	v_exp_f32_e32 v89, v89
	v_mul_f32_e32 v112, 0xbfb8aa3b, v111
	v_exp_f32_e32 v113, v112
	v_and_b32_e32 v115, 0xffff0000, v88
	v_add_f32_e32 v89, 1.0, v89
	v_rcp_f32_e32 v112, v89
	v_add_f32_e32 v89, 1.0, v113
	v_rcp_f32_e32 v113, v89
	v_pk_mul_f32 v[88:89], v[74:75], v[106:107]
	v_rcp_f32_e32 v92, v92
	v_pk_fma_f32 v[84:85], v[70:71], v[84:85], v[88:89]
	v_pk_mul_f32 v[134:135], v[110:111], v[112:113]
	v_pk_fma_f32 v[84:85], v[78:79], v[114:115], v[84:85]
	v_lshlrev_b32_e32 v112, 16, v87
	v_mul_f32_e32 v88, 0xbfb8aa3b, v84
	v_exp_f32_e32 v110, v88
	v_mul_f32_e32 v88, 0xbfb8aa3b, v85
	v_exp_f32_e32 v111, v88
	v_and_b32_e32 v113, 0xffff0000, v87
	v_pk_fma_f32 v[96:97], v[68:69], v[112:113], v[96:97]
	v_add_f32_e32 v110, 1.0, v110
	v_add_f32_e32 v111, 1.0, v111
	v_mul_f32_e32 v87, 0xbfb8aa3b, v96
	v_rcp_f32_e32 v110, v110
	v_rcp_f32_e32 v111, v111
	v_exp_f32_e32 v87, v87
	v_mul_f32_e32 v131, 0xbfb8aa3b, v97
	v_exp_f32_e32 v131, v131
	v_pk_mul_f32 v[136:137], v[84:85], v[110:111]
	v_add_f32_e32 v84, 1.0, v87
	v_lshlrev_b32_e32 v110, 16, v86
	v_and_b32_e32 v111, 0xffff0000, v86
	v_pk_mul_f32 v[86:87], v[62:63], v[116:117]
	v_rcp_f32_e32 v93, v93
	v_pk_fma_f32 v[82:83], v[58:59], v[82:83], v[86:87]
	v_add_f32_e32 v85, 1.0, v131
	v_pk_fma_f32 v[82:83], v[66:67], v[110:111], v[82:83]
	v_rcp_f32_e32 v84, v84
	v_mul_f32_e32 v86, 0xbfb8aa3b, v82
	v_mul_f32_e32 v87, 0xbfb8aa3b, v83
	v_exp_f32_e32 v86, v86
	v_exp_f32_e32 v87, v87
	v_rcp_f32_e32 v85, v85
	v_pk_mul_f32 v[90:91], v[90:91], v[92:93]
	v_add_f32_e32 v86, 1.0, v86
	v_add_f32_e32 v87, 1.0, v87
	v_rcp_f32_e32 v86, v86
	v_rcp_f32_e32 v87, v87
	v_pk_mul_f32 v[92:93], v[90:91], v[90:91]
	v_pk_mul_f32 v[140:141], v[96:97], v[84:85]
	v_pk_mul_f32 v[128:129], v[94:95], v[94:95]
	v_pk_mul_f32 v[86:87], v[82:83], v[86:87]
	v_pk_mul_f32 v[84:85], v[140:141], v[140:141]
	v_pk_mul_f32 v[82:83], v[86:87], v[86:87]
	v_mov_b32_e32 v97, v92
	v_mov_b32_e32 v96, v82
	v_mov_b32_e32 v92, v83
	v_pk_add_f32 v[82:83], v[96:97], v[92:93]
	v_mov_b32_e32 v92, v84
	v_mov_b32_e32 v93, v128
	v_pk_mul_f32 v[138:139], v[136:137], v[136:137]
	v_pk_add_f32 v[82:83], v[92:93], v[82:83]
	v_mov_b32_e32 v128, v85
	v_pk_add_f32 v[82:83], v[128:129], v[82:83]
	v_mov_b32_e32 v84, v138
	v_mov_b32_e32 v85, v126
	v_pk_mul_f32 v[88:89], v[134:135], v[134:135]
	v_pk_add_f32 v[82:83], v[84:85], v[82:83]
	v_mov_b32_e32 v126, v139
	v_pk_add_f32 v[82:83], v[126:127], v[82:83]
	v_mov_b32_e32 v84, v88
	v_mov_b32_e32 v85, v122
	v_pk_add_f32 v[82:83], v[84:85], v[82:83]
	v_mov_b32_e32 v122, v89
	v_pk_add_f32 v[82:83], v[122:123], v[82:83]
	v_mad_u64_u32 v[96:97], s[0:1], v103, s14, v[0:1]
	s_nop 0
	v_mov_b32_dpp v85, v83 quad_perm:[1,0,3,2] row_mask:0xf bank_mask:0xf bound_ctrl:1
	v_mov_b32_dpp v84, v82 quad_perm:[1,0,3,2] row_mask:0xf bank_mask:0xf bound_ctrl:1
	v_pk_add_f32 v[82:83], v[82:83], v[84:85]
	ds_write_b128 v96, v[98:101]
	v_pk_mul_f32 v[126:127], v[64:65], v[112:113]
	v_mov_b32_dpp v85, v83 quad_perm:[2,3,0,1] row_mask:0xf bank_mask:0xf bound_ctrl:1
	v_mov_b32_dpp v84, v82 quad_perm:[2,3,0,1] row_mask:0xf bank_mask:0xf bound_ctrl:1
	v_pk_add_f32 v[82:83], v[82:83], v[84:85]
	v_pk_fma_f32 v[108:109], v[60:61], v[108:109], v[126:127]
	s_movk_i32 s0, 0x48
	v_mov_b32_dpp v85, v83 row_half_mirror row_mask:0xf bank_mask:0xf bound_ctrl:1
	v_mov_b32_dpp v84, v82 row_half_mirror row_mask:0xf bank_mask:0xf bound_ctrl:1
	v_pk_add_f32 v[82:83], v[82:83], v[84:85]
	s_nop 1
	v_mov_b32_dpp v85, v83 row_mirror row_mask:0xf bank_mask:0xf bound_ctrl:1
	v_mov_b32_dpp v84, v82 row_mirror row_mask:0xf bank_mask:0xf bound_ctrl:1
	v_pk_add_f32 v[82:83], v[82:83], v[84:85]
	s_nop 0
	v_pk_add_f32 v[122:123], v[82:83], s[2:3] op_sel_hi:[1,0]
	s_nop 0
	v_mul_f32_e32 v82, 0x4b800000, v123
	v_cmp_gt_f32_e32 vcc, s72, v123
	s_nop 1
	v_cndmask_b32_e32 v82, v123, v82, vcc
	v_rsq_f32_e32 v82, v82
	s_nop 0
	v_mul_f32_e32 v0, 0x45800000, v82
	v_cndmask_b32_e32 v0, v82, v0, vcc
	v_pk_mul_f32 v[92:93], v[90:91], v[0:1] op_sel_hi:[1,0]
	v_pk_mul_f32 v[88:89], v[94:95], v[0:1] op_sel_hi:[1,0]
	v_pk_mul_f32 v[84:85], v[124:125], v[0:1] op_sel_hi:[1,0]
	v_pk_mul_f32 v[82:83], v[120:121], v[0:1] op_sel_hi:[1,0]
	v_mul_f32_e32 v0, 0x4b800000, v122
	v_cmp_gt_f32_e32 vcc, s72, v122
	v_cvt_pk_bf16_f32 v98, v92, v93
	v_cvt_pk_bf16_f32 v99, v88, v89
	v_cndmask_b32_e32 v0, v122, v0, vcc
	v_rsq_f32_e32 v0, v0
	v_cvt_pk_bf16_f32 v100, v84, v85
	v_cvt_pk_bf16_f32 v101, v82, v83
	ds_write_b128 v132, v[98:101] offset:17408
	v_pk_mul_f32 v[100:101], v[76:77], v[118:119]
	v_mul_f32_e32 v90, 0x45800000, v0
	v_pk_fma_f32 v[100:101], v[72:73], v[104:105], v[100:101]
	v_lshlrev_b32_e32 v120, 16, v57
	v_and_b32_e32 v121, 0xffff0000, v57
	v_cndmask_b32_e32 v0, v0, v90, vcc
	v_pk_fma_f32 v[100:101], v[80:81], v[120:121], v[100:101]
	v_pk_mul_f32 v[98:99], v[86:87], v[0:1] op_sel_hi:[1,0]
	v_pk_mul_f32 v[94:95], v[140:141], v[0:1] op_sel_hi:[1,0]
	v_pk_mul_f32 v[90:91], v[136:137], v[0:1] op_sel_hi:[1,0]
	v_pk_mul_f32 v[86:87], v[134:135], v[0:1] op_sel_hi:[1,0]
	v_mul_f32_e32 v0, 0xbfb8aa3b, v100
	v_exp_f32_e32 v0, v0
	v_mul_f32_e32 v57, 0xbfb8aa3b, v101
	v_exp_f32_e32 v57, v57
	v_lshlrev_b32_e32 v124, 16, v56
	v_add_f32_e32 v0, 1.0, v0
	v_rcp_f32_e32 v122, v0
	v_add_f32_e32 v0, 1.0, v57
	v_and_b32_e32 v125, 0xffff0000, v56
	v_pk_mul_f32 v[56:57], v[74:75], v[114:115]
	v_rcp_f32_e32 v123, v0
	v_pk_fma_f32 v[56:57], v[70:71], v[106:107], v[56:57]
	v_lshlrev_b32_e32 v132, 16, v54
	v_pk_fma_f32 v[56:57], v[78:79], v[124:125], v[56:57]
	v_pk_mul_f32 v[76:77], v[76:77], v[120:121]
	v_mul_f32_e32 v97, 0xbfb8aa3b, v56
	v_exp_f32_e32 v97, v97
	v_mul_f32_e32 v103, 0xbfb8aa3b, v57
	v_exp_f32_e32 v103, v103
	v_pk_fma_f32 v[72:73], v[72:73], v[118:119], v[76:77]
	v_add_f32_e32 v0, 1.0, v97
	v_rcp_f32_e32 v106, v0
	v_add_f32_e32 v0, 1.0, v103
	v_rcp_f32_e32 v107, v0
	v_lshlrev_b32_e32 v76, 16, v53
	v_and_b32_e32 v77, 0xffff0000, v53
	v_pk_fma_f32 v[72:73], v[80:81], v[76:77], v[72:73]
	v_pk_mul_f32 v[56:57], v[56:57], v[106:107]
	v_lshlrev_b32_e32 v106, 16, v55
	v_and_b32_e32 v107, 0xffff0000, v55
	v_pk_fma_f32 v[108:109], v[68:69], v[106:107], v[108:109]
	v_mul_f32_e32 v53, 0xbfb8aa3b, v72
	v_mul_f32_e32 v0, 0xbfb8aa3b, v108
	v_exp_f32_e32 v0, v0
	v_mul_f32_e32 v55, 0xbfb8aa3b, v109
	v_exp_f32_e32 v55, v55
	v_exp_f32_e32 v53, v53
	v_add_f32_e32 v0, 1.0, v0
	v_rcp_f32_e32 v128, v0
	v_add_f32_e32 v0, 1.0, v55
	v_pk_mul_f32 v[54:55], v[62:63], v[110:111]
	v_rcp_f32_e32 v129, v0
	v_pk_fma_f32 v[54:55], v[58:59], v[116:117], v[54:55]
	v_mul_f32_e32 v76, 0xbfb8aa3b, v73
	v_pk_fma_f32 v[54:55], v[66:67], v[132:133], v[54:55]
	v_exp_f32_e32 v77, v76
	v_mul_f32_e32 v0, 0xbfb8aa3b, v54
	v_exp_f32_e32 v0, v0
	v_mul_f32_e32 v97, 0xbfb8aa3b, v55
	v_exp_f32_e32 v97, v97
	v_pk_mul_f32 v[64:65], v[64:65], v[106:107]
	v_add_f32_e32 v0, 1.0, v0
	v_rcp_f32_e32 v116, v0
	v_add_f32_e32 v0, 1.0, v97
	v_rcp_f32_e32 v117, v0
	v_add_f32_e32 v0, 1.0, v53
	v_rcp_f32_e32 v76, v0
	v_add_f32_e32 v0, 1.0, v77
	v_rcp_f32_e32 v77, v0
	v_pk_fma_f32 v[60:61], v[60:61], v[112:113], v[64:65]
	v_pk_mul_f32 v[54:55], v[54:55], v[116:117]
	v_pk_mul_f32 v[108:109], v[108:109], v[128:129]
	v_pk_mul_f32 v[72:73], v[72:73], v[76:77]
	v_lshlrev_b32_e32 v76, 16, v52
	v_and_b32_e32 v77, 0xffff0000, v52
	v_pk_mul_f32 v[52:53], v[74:75], v[124:125]
	v_pk_mul_f32 v[116:117], v[54:55], v[54:55]
	v_pk_fma_f32 v[52:53], v[70:71], v[114:115], v[52:53]
	v_pk_mul_f32 v[80:81], v[108:109], v[108:109]
	v_pk_fma_f32 v[52:53], v[78:79], v[76:77], v[52:53]
	v_lshlrev_b32_e32 v76, 16, v51
	v_mul_f32_e32 v0, 0xbfb8aa3b, v52
	v_exp_f32_e32 v0, v0
	v_mul_f32_e32 v70, 0xbfb8aa3b, v53
	v_exp_f32_e32 v75, v70
	v_and_b32_e32 v77, 0xffff0000, v51
	v_add_f32_e32 v0, 1.0, v0
	v_rcp_f32_e32 v74, v0
	v_add_f32_e32 v0, 1.0, v75
	v_pk_fma_f32 v[60:61], v[68:69], v[76:77], v[60:61]
	v_rcp_f32_e32 v75, v0
	v_mul_f32_e32 v0, 0xbfb8aa3b, v60
	v_exp_f32_e32 v0, v0
	v_mul_f32_e32 v51, 0xbfb8aa3b, v61
	v_exp_f32_e32 v51, v51
	v_pk_mul_f32 v[64:65], v[52:53], v[74:75]
	v_add_f32_e32 v0, 1.0, v0
	v_rcp_f32_e32 v52, v0
	v_add_f32_e32 v0, 1.0, v51
	v_lshlrev_b32_e32 v68, 16, v50
	v_and_b32_e32 v69, 0xffff0000, v50
	v_pk_mul_f32 v[50:51], v[62:63], v[132:133]
	v_pk_mul_f32 v[126:127], v[56:57], v[56:57]
	v_pk_fma_f32 v[50:51], v[58:59], v[110:111], v[50:51]
	v_pk_mul_f32 v[62:63], v[64:65], v[64:65]
	v_pk_fma_f32 v[50:51], v[66:67], v[68:69], v[50:51]
	v_mov_b32_e32 v67, v116
	v_mul_f32_e32 v53, 0xbfb8aa3b, v50
	v_exp_f32_e32 v58, v53
	v_mul_f32_e32 v53, 0xbfb8aa3b, v51
	v_exp_f32_e32 v59, v53
	v_rcp_f32_e32 v53, v0
	v_add_f32_e32 v0, 1.0, v58
	v_rcp_f32_e32 v58, v0
	v_add_f32_e32 v0, 1.0, v59
	v_rcp_f32_e32 v59, v0
	v_pk_mul_f32 v[60:61], v[60:61], v[52:53]
	v_pk_mul_f32 v[100:101], v[100:101], v[122:123]
	v_pk_mul_f32 v[52:53], v[60:61], v[60:61]
	v_pk_mul_f32 v[58:59], v[50:51], v[58:59]
	v_pk_mul_f32 v[122:123], v[100:101], v[100:101]
	v_pk_mul_f32 v[50:51], v[58:59], v[58:59]
	v_pk_mul_f32 v[70:71], v[72:73], v[72:73]
	v_mov_b32_e32 v66, v50
	v_mov_b32_e32 v116, v51
	v_pk_add_f32 v[50:51], v[66:67], v[116:117]
	v_mov_b32_e32 v66, v52
	v_mov_b32_e32 v67, v80
	v_pk_add_f32 v[50:51], v[66:67], v[50:51]
	v_mov_b32_e32 v80, v53
	v_pk_add_f32 v[50:51], v[80:81], v[50:51]
	v_mov_b32_e32 v52, v62
	v_mov_b32_e32 v53, v126
	v_pk_add_f32 v[50:51], v[52:53], v[50:51]
	v_mov_b32_e32 v126, v63
	v_pk_add_f32 v[50:51], v[126:127], v[50:51]
	v_mov_b32_e32 v52, v70
	v_mov_b32_e32 v53, v122
	v_pk_add_f32 v[50:51], v[52:53], v[50:51]
	v_mov_b32_e32 v122, v71
	v_pk_add_f32 v[50:51], v[122:123], v[50:51]
	v_cvt_pk_bf16_f32 v104, v98, v99
	v_cvt_pk_bf16_f32 v105, v94, v95
	v_mov_b32_dpp v53, v51 quad_perm:[1,0,3,2] row_mask:0xf bank_mask:0xf bound_ctrl:1
	v_mov_b32_dpp v52, v50 quad_perm:[1,0,3,2] row_mask:0xf bank_mask:0xf bound_ctrl:1
	v_pk_add_f32 v[50:51], v[50:51], v[52:53]
	v_cvt_pk_bf16_f32 v106, v90, v91
	v_cvt_pk_bf16_f32 v107, v86, v87
	v_mov_b32_dpp v53, v51 quad_perm:[2,3,0,1] row_mask:0xf bank_mask:0xf bound_ctrl:1
	v_mov_b32_dpp v52, v50 quad_perm:[2,3,0,1] row_mask:0xf bank_mask:0xf bound_ctrl:1
	v_pk_add_f32 v[50:51], v[50:51], v[52:53]
	ds_write_b128 v130, v[104:107] offset:17408
	s_nop 0
	v_mov_b32_dpp v53, v51 row_half_mirror row_mask:0xf bank_mask:0xf bound_ctrl:1
	v_mov_b32_dpp v52, v50 row_half_mirror row_mask:0xf bank_mask:0xf bound_ctrl:1
	v_pk_add_f32 v[50:51], v[50:51], v[52:53]
	s_nop 1
	v_mov_b32_dpp v53, v51 row_mirror row_mask:0xf bank_mask:0xf bound_ctrl:1
	v_mov_b32_dpp v52, v50 row_mirror row_mask:0xf bank_mask:0xf bound_ctrl:1
	v_pk_add_f32 v[50:51], v[50:51], v[52:53]
	s_nop 0
	v_pk_add_f32 v[52:53], v[50:51], s[2:3] op_sel_hi:[1,0]
	s_nop 0
	v_mul_f32_e32 v0, 0x4b800000, v53
	v_cmp_gt_f32_e32 vcc, s72, v53
	s_nop 1
	v_cndmask_b32_e32 v0, v53, v0, vcc
	v_rsq_f32_e32 v0, v0
	s_nop 0
	v_mul_f32_e32 v50, 0x45800000, v0
	v_cndmask_b32_e32 v0, v0, v50, vcc
	v_pk_mul_f32 v[54:55], v[54:55], v[0:1] op_sel_hi:[1,0]
	v_pk_mul_f32 v[62:63], v[108:109], v[0:1] op_sel_hi:[1,0]
	v_pk_mul_f32 v[56:57], v[56:57], v[0:1] op_sel_hi:[1,0]
	v_pk_mul_f32 v[66:67], v[100:101], v[0:1] op_sel_hi:[1,0]
	v_mul_f32_e32 v0, 0x4b800000, v52
	v_cmp_gt_f32_e32 vcc, s72, v52
	v_cvt_pk_bf16_f32 v50, v54, v55
	v_cvt_pk_bf16_f32 v51, v62, v63
	v_cndmask_b32_e32 v0, v52, v0, vcc
	v_rsq_f32_e32 v0, v0
	v_cvt_pk_bf16_f32 v52, v56, v57
	v_cvt_pk_bf16_f32 v53, v66, v67
	ds_write_b128 v102, v[50:53] offset:17408
	v_mul_f32_e32 v50, 0x45800000, v0
	v_cndmask_b32_e32 v0, v0, v50, vcc
	v_pk_mul_f32 v[58:59], v[58:59], v[0:1] op_sel_hi:[1,0]
	v_pk_mul_f32 v[60:61], v[60:61], v[0:1] op_sel_hi:[1,0]
	v_pk_mul_f32 v[64:65], v[64:65], v[0:1] op_sel_hi:[1,0]
	v_pk_mul_f32 v[68:69], v[72:73], v[0:1] op_sel_hi:[1,0]
	v_cvt_pk_bf16_f32 v50, v58, v59
	v_cvt_pk_bf16_f32 v51, v60, v61
	v_cvt_pk_bf16_f32 v52, v64, v65
	v_cvt_pk_bf16_f32 v53, v68, v69
	ds_write_b128 v96, v[50:53] offset:17408
	v_cndmask_b32_e64 v0, v58, v92, s[44:45]
	v_cndmask_b32_e64 v50, v54, v98, s[44:45]
	v_cndmask_b32_e64 v51, v98, v54, s[44:45]
	v_cndmask_b32_e64 v52, v92, v58, s[44:45]
	v_cvt_pk_bf16_f32 v50, v0, v50
	v_mad_u32_u24 v0, v167, s0, v169
	v_cvt_pk_bf16_f32 v51, v51, v52
	v_lshl_add_u32 v0, v0, 1, v146
	v_cndmask_b32_e64 v52, v59, v93, s[44:45]
	v_cndmask_b32_e64 v53, v55, v99, s[44:45]
	v_cndmask_b32_e64 v54, v99, v55, s[44:45]
	v_cndmask_b32_e64 v55, v93, v59, s[44:45]
	v_cvt_pk_bf16_f32 v52, v52, v53
	v_cvt_pk_bf16_f32 v53, v54, v55
	v_add_u32_e32 v70, 0x8800, v0
	ds_write2_b64 v70, v[50:51], v[52:53] offset1:18
	v_cndmask_b32_e64 v50, v60, v88, s[44:45]
	v_cndmask_b32_e64 v51, v62, v94, s[44:45]
	v_cndmask_b32_e64 v52, v94, v62, s[44:45]
	v_cndmask_b32_e64 v53, v88, v60, s[44:45]
	v_cvt_pk_bf16_f32 v50, v50, v51
	v_cvt_pk_bf16_f32 v51, v52, v53
	v_cndmask_b32_e64 v52, v61, v89, s[44:45]
	v_cndmask_b32_e64 v53, v63, v95, s[44:45]
	v_cndmask_b32_e64 v54, v95, v63, s[44:45]
	v_cndmask_b32_e64 v55, v89, v61, s[44:45]
	v_cvt_pk_bf16_f32 v52, v52, v53
	v_cvt_pk_bf16_f32 v53, v54, v55
	ds_write2_b64 v70, v[50:51], v[52:53] offset0:36 offset1:54
	v_cndmask_b32_e64 v50, v64, v84, s[44:45]
	v_cndmask_b32_e64 v51, v56, v90, s[44:45]
	v_cndmask_b32_e64 v52, v90, v56, s[44:45]
	v_cndmask_b32_e64 v53, v84, v64, s[44:45]
	v_cvt_pk_bf16_f32 v50, v50, v51
	v_cvt_pk_bf16_f32 v51, v52, v53
	v_cndmask_b32_e64 v52, v65, v85, s[44:45]
	v_cndmask_b32_e64 v53, v57, v91, s[44:45]
	v_cndmask_b32_e64 v54, v91, v57, s[44:45]
	v_cndmask_b32_e64 v55, v85, v65, s[44:45]
	v_cvt_pk_bf16_f32 v52, v52, v53
	v_cvt_pk_bf16_f32 v53, v54, v55
	v_lshlrev_b32_e32 v54, 16, v10
	v_lshlrev_b32_e32 v56, 16, v6
	v_mov_b32_e32 v57, v54
	v_lshlrev_b32_e32 v55, 16, v2
	v_mov_b32_e32 v58, v56
	s_waitcnt vmcnt(3)
	v_pk_mul_f32 v[56:57], v[42:43], v[56:57] op_sel_hi:[0,1]
	ds_write2_b64 v70, v[50:51], v[52:53] offset0:72 offset1:90
	v_cndmask_b32_e64 v50, v68, v82, s[44:45]
	v_cndmask_b32_e64 v51, v66, v86, s[44:45]
	v_cndmask_b32_e64 v52, v86, v66, s[44:45]
	v_cndmask_b32_e64 v53, v82, v68, s[44:45]
	v_lshlrev_b32_e32 v59, 16, v18
	v_pk_fma_f32 v[54:55], v[38:39], v[54:55], v[56:57] op_sel_hi:[0,1,1]
	v_cvt_pk_bf16_f32 v50, v50, v51
	v_cvt_pk_bf16_f32 v51, v52, v53
	v_cndmask_b32_e64 v52, v69, v83, s[44:45]
	v_cndmask_b32_e64 v53, v67, v87, s[44:45]
	s_waitcnt vmcnt(1)
	v_pk_fma_f32 v[54:55], v[46:47], v[58:59], v[54:55] op_sel:[0,1,0] op_sel_hi:[0,0,1]
	v_cvt_pk_bf16_f32 v52, v52, v53
	v_mul_f32_e32 v53, 0xbfb8aa3b, v55
	v_exp_f32_e32 v53, v53
	v_mul_f32_e32 v56, 0xbfb8aa3b, v54
	v_exp_f32_e32 v56, v56
	v_lshlrev_b32_e32 v61, 16, v14
	v_mov_b32_e32 v60, v59
	v_add_f32_e32 v53, 1.0, v53
	v_rcp_f32_e32 v63, v53
	v_add_f32_e32 v53, 1.0, v56
	v_mov_b32_e32 v56, v61
	v_pk_mul_f32 v[60:61], v[42:43], v[60:61] op_sel_hi:[0,1]
	v_lshlrev_b32_e32 v57, 16, v22
	v_pk_fma_f32 v[58:59], v[38:39], v[58:59], v[60:61] op_sel_hi:[0,1,1]
	v_pk_fma_f32 v[56:57], v[46:47], v[56:57], v[58:59] op_sel_hi:[0,1,1]
	v_mul_f32_e32 v58, 0xbfb8aa3b, v56
	v_exp_f32_e32 v58, v58
	v_mul_f32_e32 v59, 0xbfb8aa3b, v57
	v_exp_f32_e32 v59, v59
	v_rcp_f32_e32 v62, v53
	v_add_f32_e32 v53, 1.0, v58
	v_rcp_f32_e32 v58, v53
	v_add_f32_e32 v53, 1.0, v59
	v_rcp_f32_e32 v59, v53
	v_cndmask_b32_e64 v64, v87, v67, s[44:45]
	v_cndmask_b32_e64 v65, v83, v69, s[44:45]
	v_cvt_pk_bf16_f32 v53, v64, v65
	ds_write2_b64 v70, v[50:51], v[52:53] offset0:108 offset1:126
	v_pk_mul_f32 v[50:51], v[54:55], v[62:63]
	v_pk_mul_f32 v[52:53], v[56:57], v[58:59]
	v_and_b32_e32 v55, 0xffff0000, v18
	v_cndmask_b32_e64 v61, v52, v50, s[44:45]
	v_cndmask_b32_e64 v63, v50, v52, s[44:45]
	v_and_b32_e32 v50, 0xffff0000, v10
	v_cndmask_b32_e64 v60, v53, v51, s[44:45]
	v_cndmask_b32_e64 v62, v51, v53, s[44:45]
	v_and_b32_e32 v52, 0xffff0000, v6
	v_mov_b32_e32 v53, v50
	v_and_b32_e32 v51, 0xffff0000, v2
	v_mov_b32_e32 v54, v52
	v_pk_mul_f32 v[52:53], v[42:43], v[52:53] op_sel:[1,0]
	v_and_b32_e32 v57, 0xffff0000, v14
	v_pk_fma_f32 v[50:51], v[38:39], v[50:51], v[52:53] op_sel:[1,0,0]
	v_mov_b32_e32 v56, v55
	v_pk_fma_f32 v[50:51], v[46:47], v[54:55], v[50:51] op_sel:[1,1,0] op_sel_hi:[1,0,1]
	v_pk_mul_f32 v[42:43], v[42:43], v[56:57] op_sel:[1,0]
	v_mul_f32_e32 v2, 0xbfb8aa3b, v51
	v_exp_f32_e32 v2, v2
	v_mul_f32_e32 v6, 0xbfb8aa3b, v50
	v_exp_f32_e32 v6, v6
	v_and_b32_e32 v53, 0xffff0000, v22
	v_mov_b32_e32 v52, v57
	v_pk_fma_f32 v[38:39], v[38:39], v[54:55], v[42:43] op_sel:[1,0,0]
	v_add_f32_e32 v2, 1.0, v2
	v_pk_fma_f32 v[38:39], v[46:47], v[52:53], v[38:39] op_sel:[1,0,0]
	v_rcp_f32_e32 v59, v2
	v_add_f32_e32 v2, 1.0, v6
	v_mul_f32_e32 v6, 0xbfb8aa3b, v38
	v_exp_f32_e32 v6, v6
	v_mul_f32_e32 v10, 0xbfb8aa3b, v39
	v_exp_f32_e32 v10, v10
	v_rcp_f32_e32 v58, v2
	v_add_f32_e32 v2, 1.0, v6
	v_rcp_f32_e32 v42, v2
	v_add_f32_e32 v2, 1.0, v10
	v_rcp_f32_e32 v43, v2
	v_pk_mul_f32 v[50:51], v[50:51], v[58:59]
	v_lshlrev_b32_e32 v53, 16, v19
	v_lshlrev_b32_e32 v55, 16, v15
	v_pk_mul_f32 v[38:39], v[38:39], v[42:43]
	v_lshlrev_b32_e32 v42, 16, v11
	v_cndmask_b32_e64 v2, v39, v51, s[44:45]
	v_cndmask_b32_e64 v6, v38, v50, s[44:45]
	v_cndmask_b32_e64 v10, v51, v39, s[44:45]
	v_cndmask_b32_e64 v14, v50, v38, s[44:45]
	v_lshlrev_b32_e32 v50, 16, v7
	v_mov_b32_e32 v51, v42
	v_lshlrev_b32_e32 v43, 16, v3
	v_mov_b32_e32 v52, v50
	v_pk_mul_f32 v[50:51], v[44:45], v[50:51] op_sel_hi:[0,1]
	v_pk_fma_f32 v[42:43], v[40:41], v[42:43], v[50:51] op_sel_hi:[0,1,1]
	v_pk_fma_f32 v[42:43], v[48:49], v[52:53], v[42:43] op_sel:[0,1,0] op_sel_hi:[0,0,1]
	v_cvt_pk_bf16_f32 v38, v2, v6
	v_mul_f32_e32 v2, 0xbfb8aa3b, v43
	v_exp_f32_e32 v2, v2
	v_mul_f32_e32 v6, 0xbfb8aa3b, v42
	v_exp_f32_e32 v6, v6
	v_mov_b32_e32 v54, v53
	v_mov_b32_e32 v50, v55
	v_pk_mul_f32 v[54:55], v[44:45], v[54:55] op_sel_hi:[0,1]
	v_lshlrev_b32_e32 v51, 16, v23
	v_pk_fma_f32 v[52:53], v[40:41], v[52:53], v[54:55] op_sel_hi:[0,1,1]
	v_add_f32_e32 v2, 1.0, v2
	v_pk_fma_f32 v[50:51], v[48:49], v[50:51], v[52:53] op_sel_hi:[0,1,1]
	v_rcp_f32_e32 v57, v2
	v_add_f32_e32 v2, 1.0, v6
	v_mul_f32_e32 v6, 0xbfb8aa3b, v50
	v_cvt_pk_bf16_f32 v39, v14, v10
	v_exp_f32_e32 v6, v6
	v_mul_f32_e32 v10, 0xbfb8aa3b, v51
	v_exp_f32_e32 v10, v10
	v_rcp_f32_e32 v56, v2
	v_add_f32_e32 v2, 1.0, v6
	v_rcp_f32_e32 v52, v2
	v_add_f32_e32 v2, 1.0, v10
	v_rcp_f32_e32 v53, v2
	v_and_b32_e32 v2, 0xffff0000, v11
	v_and_b32_e32 v6, 0xffff0000, v7
	v_mov_b32_e32 v7, v2
	v_mov_b32_e32 v18, v45
	v_add_u32_e32 v40, 0xd000, v0
	v_and_b32_e32 v3, 0xffff0000, v3
	v_mov_b32_e32 v10, v6
	v_mov_b32_e32 v0, v41
	v_pk_mul_f32 v[6:7], v[18:19], v[6:7] op_sel_hi:[0,1]
	v_and_b32_e32 v11, 0xffff0000, v19
	v_pk_fma_f32 v[2:3], v[0:1], v[2:3], v[6:7] op_sel_hi:[0,1,1]
	v_mov_b32_e32 v22, v49
	v_pk_fma_f32 v[2:3], v[22:23], v[10:11], v[2:3] op_sel:[0,1,0] op_sel_hi:[0,0,1]
	v_mul_f32_e32 v6, 0xbfb8aa3b, v3
	v_exp_f32_e32 v19, v6
	v_mul_f32_e32 v6, 0xbfb8aa3b, v2
	v_and_b32_e32 v7, 0xffff0000, v23
	v_exp_f32_e32 v23, v6
	v_add_f32_e32 v19, 1.0, v19
	v_rcp_f32_e32 v19, v19
	v_and_b32_e32 v15, 0xffff0000, v15
	v_mov_b32_e32 v14, v11
	v_mov_b32_e32 v6, v15
	v_pk_mul_f32 v[14:15], v[18:19], v[14:15] op_sel_hi:[0,1]
	v_add_f32_e32 v23, 1.0, v23
	v_pk_fma_f32 v[10:11], v[0:1], v[10:11], v[14:15] op_sel_hi:[0,1,1]
	v_pk_fma_f32 v[6:7], v[22:23], v[6:7], v[10:11] op_sel_hi:[0,1,1]
	v_mul_f32_e32 v0, 0xbfb8aa3b, v6
	v_exp_f32_e32 v0, v0
	v_mul_f32_e32 v10, 0xbfb8aa3b, v7
	v_exp_f32_e32 v11, v10
	v_rcp_f32_e32 v18, v23
	v_add_f32_e32 v0, 1.0, v0
	v_rcp_f32_e32 v10, v0
	v_add_f32_e32 v0, 1.0, v11
	v_rcp_f32_e32 v11, v0
	v_pk_mul_f32 v[2:3], v[2:3], v[18:19]
	v_lshlrev_b32_e32 v19, 16, v20
	v_cvt_pk_bf16_f32 v46, v60, v61
	v_pk_mul_f32 v[6:7], v[6:7], v[10:11]
	v_cvt_pk_bf16_f32 v47, v63, v62
	v_cndmask_b32_e64 v0, v7, v3, s[44:45]
	v_cndmask_b32_e64 v10, v6, v2, s[44:45]
	v_cndmask_b32_e64 v41, v2, v6, s[44:45]
	v_lshlrev_b32_e32 v6, 16, v12
	v_cvt_pk_bf16_f32 v2, v0, v10
	v_lshlrev_b32_e32 v10, 16, v8
	v_mov_b32_e32 v11, v6
	v_cndmask_b32_e64 v3, v3, v7, s[44:45]
	v_lshlrev_b32_e32 v7, 16, v4
	v_mov_b32_e32 v18, v10
	v_pk_mul_f32 v[10:11], v[30:31], v[10:11] op_sel_hi:[0,1]
	v_pk_fma_f32 v[6:7], v[26:27], v[6:7], v[10:11] op_sel_hi:[0,1,1]
	s_waitcnt vmcnt(0)
	v_pk_fma_f32 v[6:7], v[34:35], v[18:19], v[6:7] op_sel:[0,1,0] op_sel_hi:[0,0,1]
	v_mul_f32_e32 v0, 0xbfb8aa3b, v7
	v_exp_f32_e32 v0, v0
	v_mul_f32_e32 v10, 0xbfb8aa3b, v6
	v_exp_f32_e32 v10, v10
	ds_write2_b64 v40, v[46:47], v[38:39] offset1:18
	v_pk_mul_f32 v[38:39], v[42:43], v[56:57]
	v_pk_mul_f32 v[42:43], v[50:51], v[52:53]
	v_lshlrev_b32_e32 v23, 16, v16
	v_cndmask_b32_e64 v44, v43, v39, s[44:45]
	v_cndmask_b32_e64 v46, v42, v38, s[44:45]
	v_cndmask_b32_e64 v39, v39, v43, s[44:45]
	v_cndmask_b32_e64 v38, v38, v42, s[44:45]
	v_mov_b32_e32 v22, v19
	v_add_f32_e32 v0, 1.0, v0
	v_cvt_pk_bf16_f32 v15, v38, v39
	v_rcp_f32_e32 v39, v0
	v_add_f32_e32 v0, 1.0, v10
	v_mov_b32_e32 v10, v23
	v_pk_mul_f32 v[22:23], v[30:31], v[22:23] op_sel_hi:[0,1]
	v_lshlrev_b32_e32 v11, 16, v24
	v_pk_fma_f32 v[18:19], v[26:27], v[18:19], v[22:23] op_sel_hi:[0,1,1]
	v_pk_fma_f32 v[10:11], v[34:35], v[10:11], v[18:19] op_sel_hi:[0,1,1]
	v_mul_f32_e32 v18, 0xbfb8aa3b, v10
	v_exp_f32_e32 v18, v18
	v_mul_f32_e32 v19, 0xbfb8aa3b, v11
	v_exp_f32_e32 v19, v19
	v_rcp_f32_e32 v38, v0
	v_add_f32_e32 v0, 1.0, v18
	v_rcp_f32_e32 v18, v0
	v_add_f32_e32 v0, 1.0, v19
	v_rcp_f32_e32 v19, v0
	v_cvt_pk_bf16_f32 v14, v44, v46
	v_cvt_pk_bf16_f32 v3, v41, v3
	ds_write2_b64 v40, v[14:15], v[2:3] offset0:36 offset1:54
	v_pk_mul_f32 v[2:3], v[6:7], v[38:39]
	v_pk_mul_f32 v[6:7], v[10:11], v[18:19]
	v_and_b32_e32 v11, 0xffff0000, v20
	v_cndmask_b32_e64 v22, v6, v2, s[44:45]
	v_cndmask_b32_e64 v38, v2, v6, s[44:45]
	v_and_b32_e32 v2, 0xffff0000, v12
	v_cndmask_b32_e64 v0, v7, v3, s[44:45]
	v_cndmask_b32_e64 v23, v3, v7, s[44:45]
	v_and_b32_e32 v6, 0xffff0000, v8
	v_mov_b32_e32 v7, v2
	v_and_b32_e32 v3, 0xffff0000, v4
	v_mov_b32_e32 v10, v6
	v_pk_mul_f32 v[6:7], v[30:31], v[6:7] op_sel:[1,0]
	v_and_b32_e32 v15, 0xffff0000, v16
	v_pk_fma_f32 v[2:3], v[26:27], v[2:3], v[6:7] op_sel:[1,0,0]
	v_mov_b32_e32 v14, v11
	v_pk_fma_f32 v[2:3], v[34:35], v[10:11], v[2:3] op_sel:[1,1,0] op_sel_hi:[1,0,1]
	v_and_b32_e32 v7, 0xffff0000, v24
	v_mul_f32_e32 v4, 0xbfb8aa3b, v3
	v_exp_f32_e32 v4, v4
	v_mul_f32_e32 v6, 0xbfb8aa3b, v2
	v_exp_f32_e32 v8, v6
	v_mov_b32_e32 v6, v15
	v_pk_mul_f32 v[14:15], v[30:31], v[14:15] op_sel:[1,0]
	v_add_f32_e32 v4, 1.0, v4
	v_pk_fma_f32 v[10:11], v[26:27], v[10:11], v[14:15] op_sel:[1,0,0]
	v_rcp_f32_e32 v19, v4
	v_pk_fma_f32 v[6:7], v[34:35], v[6:7], v[10:11] op_sel:[1,0,0]
	v_add_f32_e32 v4, 1.0, v8
	v_mul_f32_e32 v8, 0xbfb8aa3b, v6
	v_exp_f32_e32 v8, v8
	v_mul_f32_e32 v10, 0xbfb8aa3b, v7
	v_exp_f32_e32 v11, v10
	v_rcp_f32_e32 v18, v4
	v_add_f32_e32 v4, 1.0, v8
	v_rcp_f32_e32 v10, v4
	v_add_f32_e32 v4, 1.0, v11
	v_rcp_f32_e32 v11, v4
	v_pk_mul_f32 v[2:3], v[2:3], v[18:19]
	v_cvt_pk_bf16_f32 v14, v0, v22
	v_lshlrev_b32_e32 v19, 16, v21
	v_pk_mul_f32 v[6:7], v[6:7], v[10:11]
	v_lshlrev_b32_e32 v10, 16, v9
	v_cndmask_b32_e64 v4, v6, v2, s[44:45]
	v_cndmask_b32_e64 v8, v2, v6, s[44:45]
	v_lshlrev_b32_e32 v6, 16, v13
	v_mov_b32_e32 v11, v6
	v_cndmask_b32_e64 v0, v7, v3, s[44:45]
	v_cndmask_b32_e64 v3, v3, v7, s[44:45]
	v_lshlrev_b32_e32 v7, 16, v5
	v_mov_b32_e32 v18, v10
	v_pk_mul_f32 v[10:11], v[32:33], v[10:11] op_sel_hi:[0,1]
	v_pk_fma_f32 v[6:7], v[28:29], v[6:7], v[10:11] op_sel_hi:[0,1,1]
	v_pk_fma_f32 v[6:7], v[36:37], v[18:19], v[6:7] op_sel:[0,1,0] op_sel_hi:[0,0,1]
	v_cvt_pk_bf16_f32 v2, v0, v4
	v_mul_f32_e32 v0, 0xbfb8aa3b, v7
	v_exp_f32_e32 v0, v0
	v_mul_f32_e32 v4, 0xbfb8aa3b, v6
	v_cvt_pk_bf16_f32 v15, v38, v23
	v_lshlrev_b32_e32 v23, 16, v17
	v_exp_f32_e32 v4, v4
	v_mov_b32_e32 v22, v19
	v_mov_b32_e32 v10, v23
	v_pk_mul_f32 v[22:23], v[32:33], v[22:23] op_sel_hi:[0,1]
	v_lshlrev_b32_e32 v11, 16, v25
	v_pk_fma_f32 v[18:19], v[28:29], v[18:19], v[22:23] op_sel_hi:[0,1,1]
	v_add_f32_e32 v0, 1.0, v0
	v_pk_fma_f32 v[10:11], v[36:37], v[10:11], v[18:19] op_sel_hi:[0,1,1]
	v_rcp_f32_e32 v27, v0
	v_add_f32_e32 v0, 1.0, v4
	v_mul_f32_e32 v4, 0xbfb8aa3b, v10
	v_exp_f32_e32 v4, v4
	v_mul_f32_e32 v12, 0xbfb8aa3b, v11
	v_exp_f32_e32 v12, v12
	v_rcp_f32_e32 v26, v0
	v_add_f32_e32 v0, 1.0, v4
	v_rcp_f32_e32 v18, v0
	v_add_f32_e32 v0, 1.0, v12
	v_rcp_f32_e32 v19, v0
	v_cvt_pk_bf16_f32 v3, v8, v3
	ds_write2_b64 v40, v[14:15], v[2:3] offset0:72 offset1:90
	v_pk_mul_f32 v[2:3], v[6:7], v[26:27]
	v_pk_mul_f32 v[6:7], v[10:11], v[18:19]
	v_and_b32_e32 v4, 0xffff0000, v9
	v_cndmask_b32_e64 v15, v6, v2, s[44:45]
	v_cndmask_b32_e64 v18, v2, v6, s[44:45]
	v_and_b32_e32 v2, 0xffff0000, v13
	v_cndmask_b32_e64 v14, v7, v3, s[44:45]
	v_cndmask_b32_e64 v16, v3, v7, s[44:45]
	v_and_b32_e32 v3, 0xffff0000, v5
	v_mov_b32_e32 v5, v2
	v_mov_b32_e32 v10, v33
	v_mov_b32_e32 v6, v4
	v_mov_b32_e32 v0, v29
	v_pk_mul_f32 v[4:5], v[10:11], v[4:5] op_sel_hi:[0,1]
	v_and_b32_e32 v7, 0xffff0000, v21
	v_pk_fma_f32 v[2:3], v[0:1], v[2:3], v[4:5] op_sel_hi:[0,1,1]
	v_mov_b32_e32 v12, v37
	v_pk_fma_f32 v[2:3], v[12:13], v[6:7], v[2:3] op_sel:[0,1,0] op_sel_hi:[0,0,1]
	v_mul_f32_e32 v4, 0xbfb8aa3b, v3
	v_exp_f32_e32 v11, v4
	v_mul_f32_e32 v4, 0xbfb8aa3b, v2
	v_exp_f32_e32 v13, v4
	v_and_b32_e32 v9, 0xffff0000, v17
	v_add_f32_e32 v11, 1.0, v11
	v_rcp_f32_e32 v11, v11
	v_mov_b32_e32 v8, v7
	v_mov_b32_e32 v4, v9
	v_and_b32_e32 v5, 0xffff0000, v25
	v_pk_mul_f32 v[8:9], v[10:11], v[8:9] op_sel_hi:[0,1]
	v_add_f32_e32 v13, 1.0, v13
	v_pk_fma_f32 v[6:7], v[0:1], v[6:7], v[8:9] op_sel_hi:[0,1,1]
	v_pk_fma_f32 v[4:5], v[12:13], v[4:5], v[6:7] op_sel_hi:[0,1,1]
	v_mul_f32_e32 v0, 0xbfb8aa3b, v4
	v_exp_f32_e32 v0, v0
	v_mul_f32_e32 v6, 0xbfb8aa3b, v5
	v_exp_f32_e32 v7, v6
	v_rcp_f32_e32 v10, v13
	v_add_f32_e32 v0, 1.0, v0
	v_rcp_f32_e32 v6, v0
	v_add_f32_e32 v0, 1.0, v7
	v_rcp_f32_e32 v7, v0
	v_pk_mul_f32 v[2:3], v[2:3], v[10:11]
	v_cvt_pk_bf16_f32 v8, v14, v15
	v_cvt_pk_bf16_f32 v9, v18, v16
	v_pk_mul_f32 v[4:5], v[4:5], v[6:7]
	s_nop 0
	v_cndmask_b32_e64 v0, v5, v3, s[44:45]
	v_cndmask_b32_e64 v6, v4, v2, s[44:45]
	v_cndmask_b32_e64 v3, v3, v5, s[44:45]
	v_cndmask_b32_e64 v4, v2, v4, s[44:45]
	v_cvt_pk_bf16_f32 v2, v0, v6
	v_cvt_pk_bf16_f32 v3, v4, v3
	ds_write2_b64 v40, v[8:9], v[2:3] offset0:108 offset1:126
	s_and_saveexec_b64 s[0:1], s[46:47]
	s_cbranch_execz .LBB0_314
	v_lshl_or_b32 v0, v164, 3, v163
	v_lshlrev_b32_e32 v0, 2, v0
	s_waitcnt lgkmcnt(0)
	v_mov_b32_e32 v2, s101
	s_mov_b32 s2, 0x41a00000
	s_waitcnt vmcnt(0)
	v_add_f32_e32 v2, v166, v2
	v_cmp_nlt_f32_e32 vcc, s2, v2
	s_and_saveexec_b64 s[22:23], vcc
	s_cbranch_execz .LBB0_313
	v_mul_f32_e32 v3, 0x3fb8aa3b, v2
	v_rndne_f32_e32 v4, v3
	s_mov_b32 s2, 0x3fb8aa3b
	v_sub_f32_e32 v5, v3, v4
	v_fma_f32 v3, v2, s2, -v3
	v_fmac_f32_e32 v3, 0x32a5705f, v2
	v_add_f32_e32 v3, v5, v3
	v_cvt_i32_f32_e32 v4, v4
	v_exp_f32_e32 v3, v3
	s_mov_b32 s2, 0xc2ce8ed0
	v_cmp_ngt_f32_e32 vcc, s2, v2
	s_mov_b32 s2, 0x42b17218
	v_ldexp_f32 v3, v3, v4
	v_cndmask_b32_e32 v3, 0, v3, vcc
	v_cmp_nlt_f32_e32 vcc, s2, v2
	s_mov_b32 s2, 0x3f2aaaab
	s_nop 0
	v_cndmask_b32_e32 v16, v239, v3, vcc
	v_add_f32_e32 v4, 1.0, v16
	v_add_f32_e32 v2, -1.0, v4
	v_sub_f32_e32 v3, v2, v4
	v_add_f32_e32 v3, 1.0, v3
	v_sub_f32_e32 v2, v16, v2
	v_add_f32_e32 v5, v2, v3
	v_frexp_mant_f32_e32 v6, v4
	v_cvt_f64_f32_e32 v[2:3], v4
	v_frexp_exp_i32_f64_e32 v2, v[2:3]
	v_cmp_gt_f32_e32 vcc, s2, v6
	s_mov_b32 s2, 0x3f317218
	s_nop 0
	v_subbrev_co_u32_e32 v10, vcc, 0, v2, vcc
	v_sub_u32_e32 v2, 0, v10
	v_ldexp_f32 v3, v4, v2
	v_add_f32_e32 v4, -1.0, v3
	v_add_f32_e32 v6, 1.0, v3
	v_ldexp_f32 v2, v5, v2
	v_add_f32_e32 v5, 1.0, v4
	v_add_f32_e32 v7, -1.0, v6
	v_sub_f32_e32 v5, v3, v5
	v_sub_f32_e32 v3, v3, v7
	v_add_f32_e32 v5, v2, v5
	v_add_f32_e32 v2, v2, v3
	v_add_f32_e32 v11, v6, v2
	v_rcp_f32_e32 v13, v11
	v_sub_f32_e32 v3, v6, v11
	v_add_f32_e32 v12, v2, v3
	v_add_f32_e32 v3, v4, v5
	v_mul_f32_e32 v15, v3, v13
	v_sub_f32_e32 v2, v4, v3
	v_mul_f32_e32 v4, v11, v15
	v_fma_f32 v6, v15, v11, -v4
	v_fmac_f32_e32 v6, v15, v12
	v_add_f32_e32 v14, v5, v2
	v_add_f32_e32 v2, v4, v6
	v_sub_f32_e32 v5, v3, v2
	v_pk_add_f32 v[8:9], v[2:3], v[4:5] neg_lo:[0,1] neg_hi:[0,1]
	v_mov_b32_e32 v7, v2
	v_pk_add_f32 v[2:3], v[8:9], v[6:7] neg_lo:[0,1] neg_hi:[0,1]
	s_nop 0
	v_add_f32_e32 v3, v14, v3
	v_add_f32_e32 v2, v2, v3
	v_add_f32_e32 v3, v5, v2
	v_mul_f32_e32 v14, v13, v3
	v_mul_f32_e32 v4, v11, v14
	v_fma_f32 v6, v14, v11, -v4
	v_fmac_f32_e32 v6, v14, v12
	v_sub_f32_e32 v5, v5, v3
	v_add_f32_e32 v11, v2, v5
	v_add_f32_e32 v2, v4, v6
	v_sub_f32_e32 v5, v3, v2
	v_pk_add_f32 v[8:9], v[2:3], v[4:5] neg_lo:[0,1] neg_hi:[0,1]
	v_mov_b32_e32 v7, v2
	v_pk_add_f32 v[2:3], v[8:9], v[6:7] neg_lo:[0,1] neg_hi:[0,1]
	s_nop 0
	v_add_f32_e32 v3, v11, v3
	v_add_f32_e32 v2, v2, v3
	v_add_f32_e32 v3, v15, v14
	v_add_f32_e32 v2, v5, v2
	v_sub_f32_e32 v4, v3, v15
	v_mul_f32_e32 v2, v13, v2
	v_sub_f32_e32 v4, v14, v4
	v_add_f32_e32 v4, v4, v2
	v_add_f32_e32 v6, v3, v4
	v_mul_f32_e32 v7, v6, v6
	v_fmamk_f32 v2, v7, 0x3e9b6dac, v231
	v_fmaak_f32 v203, v7, v2, 0x3f2aaada
	v_cvt_f32_i32_e32 v2, v10
	v_sub_f32_e32 v3, v6, v3
	v_sub_f32_e32 v3, v4, v3
	v_ldexp_f32 v8, v3, 1
	v_mul_f32_e32 v3, v6, v7
	v_ldexp_f32 v5, v6, 1
	v_pk_mul_f32 v[6:7], v[2:3], v[202:203]
	s_nop 0
	v_fma_f32 v4, v2, s2, -v6
	v_fmac_f32_e32 v4, 0xb102e308, v2
	v_pk_add_f32 v[2:3], v[6:7], v[4:5]
	s_mov_b32 s2, 0x7f800000
	v_sub_f32_e32 v5, v3, v5
	v_sub_f32_e32 v5, v7, v5
	v_add_f32_e32 v9, v8, v5
	v_mov_b32_e32 v8, v6
	v_pk_add_f32 v[6:7], v[2:3], v[6:7] neg_lo:[0,1] neg_hi:[0,1]
	v_pk_add_f32 v[10:11], v[2:3], v[8:9]
	v_mov_b32_e32 v5, v2
	v_mov_b32_e32 v7, v11
	v_pk_add_f32 v[12:13], v[4:5], v[6:7] neg_lo:[0,1] neg_hi:[0,1]
	v_pk_add_f32 v[4:5], v[4:5], v[6:7]
	v_mov_b32_e32 v8, v9
	v_pk_add_f32 v[6:7], v[4:5], v[2:3] op_sel:[1,0] op_sel_hi:[0,1] neg_lo:[0,1] neg_hi:[0,1]
	v_pk_add_f32 v[14:15], v[10:11], v[6:7] op_sel_hi:[1,0] neg_lo:[0,1] neg_hi:[0,1]
	v_mov_b32_e32 v10, v11
	v_mov_b32_e32 v11, v5
	v_pk_mov_b32 v[6:7], v[2:3], v[6:7] op_sel:[1,0]
	v_mov_b32_e32 v9, v2
	v_pk_add_f32 v[6:7], v[10:11], v[6:7] neg_lo:[0,1] neg_hi:[0,1]
	v_mov_b32_e32 v14, v12
	v_pk_add_f32 v[2:3], v[8:9], v[6:7] neg_lo:[0,1] neg_hi:[0,1]
	v_mov_b32_e32 v13, v5
	v_pk_add_f32 v[6:7], v[14:15], v[2:3]
	v_cmp_neq_f32_e32 vcc, s2, v16
	v_pk_add_f32 v[8:9], v[6:7], v[6:7] op_sel:[0,1] op_sel_hi:[1,0]
	s_mov_b32 s2, 0x33800000
	v_pk_add_f32 v[4:5], v[4:5], v[8:9] op_sel:[1,0] op_sel_hi:[0,1]
	v_mov_b32_e32 v7, v4
	v_pk_add_f32 v[10:11], v[6:7], v[12:13] neg_lo:[0,1] neg_hi:[0,1]
	v_mov_b32_e32 v3, v8
	v_sub_f32_e32 v5, v6, v10
	v_pk_add_f32 v[2:3], v[2:3], v[10:11] neg_lo:[0,1] neg_hi:[0,1]
	v_sub_f32_e32 v5, v12, v5
	v_add_f32_e32 v2, v2, v5
	v_add_f32_e32 v2, v2, v3
	v_add_f32_e32 v2, v4, v2
	v_cndmask_b32_e32 v2, v239, v2, vcc
	v_cmp_lt_f32_e64 vcc, |v16|, s2
	s_nop 1
	v_cndmask_b32_e32 v2, v2, v16, vcc
.LBB0_313:
	s_or_b64 exec, exec, s[22:23]
	v_mov_b32_e32 v0, s100
	v_mul_f32_e32 v165, 0xbfb8aa3b, v165
	s_mov_b32 s2, 0x3fb8aa3b
	v_exp_f32_e32 v3, v165
	s_waitcnt vmcnt(0)
	v_mul_f32_e32 v4, 0x3fb8aa3b, v0
	v_fma_f32 v5, v0, s2, -v4
	v_rndne_f32_e32 v6, v4
	v_fmac_f32_e32 v5, 0x32a5705f, v0
	v_sub_f32_e32 v4, v4, v6
	v_add_f32_e32 v4, v4, v5
	v_exp_f32_e32 v4, v4
	v_cvt_i32_f32_e32 v5, v6
	s_mov_b32 s2, 0xc2ce8ed0
	v_cmp_ngt_f32_e32 vcc, s2, v0
	s_mov_b32 s2, 0x42b17218
	v_ldexp_f32 v4, v4, v5
	v_cndmask_b32_e32 v4, 0, v4, vcc
	v_cmp_nlt_f32_e32 vcc, s2, v0
	v_and_b32_e32 v5, 64, v238
	v_add_u32_e32 v6, -1, v238
	v_cndmask_b32_e32 v0, v239, v4, vcc
	v_cmp_lt_i32_e32 vcc, v6, v5
	v_mul_f32_e64 v4, v2, -v0
	v_add_f32_e32 v3, 1.0, v3
	v_cndmask_b32_e32 v6, v6, v238, vcc
	v_lshlrev_b32_e32 v6, 2, v6
	ds_bpermute_b32 v6, v6, v4
	v_cmp_eq_u32_e32 vcc, 0, v160
	v_rcp_f32_e32 v3, v3
	s_waitcnt lgkmcnt(0)
	v_fma_f32 v0, v2, -v0, v6
	v_add_u32_e32 v2, -2, v238
	v_cndmask_b32_e32 v0, v0, v4, vcc
	v_cmp_lt_i32_e32 vcc, v2, v5
	s_nop 1
	v_cndmask_b32_e32 v2, v2, v238, vcc
	v_lshlrev_b32_e32 v2, 2, v2
	ds_bpermute_b32 v2, v2, v0
	v_cmp_gt_u32_e32 vcc, 2, v160
	s_waitcnt lgkmcnt(0)
	v_add_f32_e32 v2, v0, v2
	v_cndmask_b32_e32 v0, v2, v0, vcc
	v_add_u32_e32 v2, -4, v238
	v_cmp_lt_i32_e32 vcc, v2, v5
	s_nop 1
	v_cndmask_b32_e32 v2, v2, v238, vcc
	v_lshlrev_b32_e32 v2, 2, v2
	ds_bpermute_b32 v2, v2, v0
	v_cmp_gt_u32_e32 vcc, 4, v160
	s_waitcnt lgkmcnt(0)
	v_add_f32_e32 v2, v0, v2
	v_cndmask_b32_e32 v0, v2, v0, vcc
	v_add_u32_e32 v2, -8, v238
	v_cmp_lt_i32_e32 vcc, v2, v5
	s_nop 1
	v_cndmask_b32_e32 v2, v2, v238, vcc
	v_lshlrev_b32_e32 v2, 2, v2
	ds_bpermute_b32 v2, v2, v0
	v_cmp_gt_u32_e32 vcc, 8, v160
	s_waitcnt lgkmcnt(0)
	v_add_f32_e32 v2, v0, v2
	v_cndmask_b32_e32 v0, v2, v0, vcc
	v_add_u32_e32 v2, -16, v238
	v_cmp_lt_i32_e32 vcc, v2, v5
	s_nop 1
	v_cndmask_b32_e32 v2, v2, v238, vcc
	v_lshlrev_b32_e32 v2, 2, v2
	ds_bpermute_b32 v2, v2, v0
	v_cmp_gt_u32_e32 vcc, 16, v160
	s_waitcnt lgkmcnt(0)
	v_add_f32_e32 v2, v0, v2
	v_cndmask_b32_e32 v0, v2, v0, vcc
	v_subrev_u32_e32 v2, 32, v238
	v_cmp_lt_i32_e32 vcc, v2, v5
	s_nop 1
	v_cndmask_b32_e32 v2, v2, v238, vcc
	v_lshlrev_b32_e32 v2, 2, v2
	ds_bpermute_b32 v2, v2, v0
	v_cmp_gt_u32_e32 vcc, 32, v160
	s_waitcnt lgkmcnt(0)
	v_add_f32_e32 v2, v0, v2
	v_cndmask_b32_e32 v0, v2, v0, vcc
	v_lshl_add_u32 v2, v160, 2, v157
	ds_write_b32 v2, v3
	v_lshl_add_u32 v2, v148, 2, v157
	ds_write_b32 v2, v0 offset:256

.LBB0_555:
	s_or_b64 exec, exec, s[0:1]
	v_readlane_b32 s0, v254, 22
	s_waitcnt lgkmcnt(0)
	s_barrier
	s_nop 0
	v_mov_b32_e32 v0, s0
	ds_read_b32 v0, v0
	v_readlane_b32 s0, v254, 49
	s_waitcnt lgkmcnt(0)
	s_nop 0
	v_cmp_le_u32_e32 vcc, s0, v0
	s_mov_b64 s[0:1], -1
	s_cbranch_vccnz .LBB0_550
	v_lshl_add_u32 v0, v0, 1, v147
	v_sub_u32_e32 v3, 0, v0
	v_max_i32_e32 v3, v0, v3
	v_mul_hi_u32 v4, v3, v247
	v_mul_lo_u32 v5, v4, s17
	v_sub_u32_e32 v3, v3, v5
	v_add_u32_e32 v5, 1, v4
	v_cmp_le_u32_e32 vcc, s17, v3
	v_ashrrev_i32_e32 v2, 31, v0
	v_readlane_b32 s0, v254, 33
	v_cndmask_b32_e32 v4, v4, v5, vcc
	v_subrev_u32_e32 v5, s17, v3
	v_cndmask_b32_e32 v3, v3, v5, vcc
	v_add_u32_e32 v5, 1, v4
	v_cmp_le_u32_e32 vcc, s17, v3
	v_mov_b32_e32 v148, v156
	v_bfrev_b32_e32 v165, 1
	v_cndmask_b32_e32 v3, v4, v5, vcc
	v_xor_b32_e32 v3, v3, v2
	v_sub_u32_e32 v162, v3, v2
	v_mul_lo_u32 v2, v162, s17
	v_sub_u32_e32 v161, v0, v2
	v_and_b32_e32 v164, 1, v162
	v_add_u32_e32 v2, s0, v161
	v_ashrrev_i32_e32 v0, 4, v162
	v_sub_u32_e32 v3, s36, v2
	v_cmp_eq_u32_e64 s[44:45], 0, v164
	v_readlane_b32 s0, v254, 31
	v_readlane_b32 s1, v254, 32
	v_cndmask_b32_e64 v2, v3, v2, s[44:45]
	v_lshl_add_u32 v3, v0, 8, v246
	v_lshlrev_b32_e32 v0, 12, v0
	v_cndmask_b32_e64 v26, v0, v3, s[0:1]
	v_bfe_u32 v163, v162, 1, 3
	v_ashrrev_i32_e32 v27, 31, v26
	v_lshlrev_b32_e32 v4, 6, v2
	v_cmp_gt_u32_e64 s[46:47], 64, v148
	v_lshl_or_b32 v130, v164, 3, v163
	v_lshlrev_b32_e32 v130, 2, v130
	s_nop 0
	v_readfirstlane_b32 s100, v130
	s_nop 4
	s_load_dword s101, s[82:83], s100
	s_load_dword s100, s[80:81], s100
	v_mov_b32_e32 v130, 0
	v_mov_b32_e32 v166, 0
	s_and_saveexec_b64 s[0:1], s[46:47]
	s_cbranch_execz .LBB0_558
	v_xor_b32_e32 v0, 63, v148
	v_ashrrev_i32_e32 v5, 31, v4
	v_cndmask_b32_e64 v0, v0, v148, s[44:45]
	v_lshl_add_u64 v[2:3], v[4:5], 0, v[26:27]
	v_or_b32_e32 v2, v2, v0
	v_readlane_b32 s22, v251, 58
	v_lshlrev_b64 v[2:3], 7, v[2:3]
	v_readlane_b32 s23, v251, 59
	v_lshlrev_b32_e32 v0, 5, v164
	s_nop 0
	v_lshl_add_u64 v[2:3], s[22:23], 0, v[2:3]
	v_lshl_add_u64 v[2:3], v[2:3], 0, v[0:1]
	v_lshlrev_b32_e32 v0, 2, v163
	v_lshl_add_u64 v[2:3], v[2:3], 0, v[0:1]
	global_load_dword v165, v[2:3], off
	global_load_dword v166, v[2:3], off offset:64

.LBB0_594:
	s_or_b64 exec, exec, s[0:1]
	v_lshlrev_b32_e32 v0, 2, v32
	v_lshl_add_u64 v[34:35], s[78:79], 0, v[0:1]
	s_movk_i32 s0, 0x3000
	v_add_co_u32_e32 v32, vcc, s0, v34
	s_mov_b64 s[0:1], 0x6000
	global_load_dwordx4 v[26:29], v0, s[78:79] offset:16
	global_load_dwordx4 v[38:41], v0, s[78:79]
	v_addc_co_u32_e32 v33, vcc, 0, v35, vcc
	v_lshl_add_u64 v[36:37], v[34:35], 0, s[0:1]
	s_movk_i32 s0, 0x6000
	v_sub_u32_e32 v0, 60, v168
	v_lshl_add_u64 v[30:31], v[34:35], 0, s[24:25]
	v_add_co_u32_e32 v34, vcc, s0, v34
	v_cndmask_b32_e64 v0, v0, v168, s[44:45]
	v_and_b32_e32 v150, 56, v150
	s_mov_b32 s0, 0x7ffffff8
	v_bitop3_b32 v150, v0, v150, s0 bitop3:0x6c
	s_waitcnt vmcnt(14)
	v_lshlrev_b32_e32 v154, 16, v145
	v_and_b32_e32 v155, 0xffff0000, v145
	v_and_or_b32 v169, v0, 4, v150
	v_lshlrev_b32_e32 v150, 16, v133
	v_and_b32_e32 v151, 0xffff0000, v133
	s_waitcnt vmcnt(10)
	v_pk_mul_f32 v[152:153], v[124:125], v[154:155]
	v_lshlrev_b32_e32 v172, 16, v132
	v_pk_fma_f32 v[152:153], v[120:121], v[150:151], v[152:153]
	v_lshlrev_b32_e32 v150, 16, v141
	v_and_b32_e32 v151, 0xffff0000, v141
	s_waitcnt vmcnt(8)
	v_pk_fma_f32 v[152:153], v[128:129], v[150:151], v[152:153]
	v_and_b32_e32 v173, 0xffff0000, v132
	v_mul_f32_e32 v0, 0xbfb8aa3b, v152
	v_exp_f32_e32 v133, v0
	v_mul_f32_e32 v0, 0xbfb8aa3b, v153
	v_exp_f32_e32 v141, v0
	v_lshlrev_b32_e32 v132, 16, v144
	v_add_f32_e32 v133, 1.0, v133
	v_rcp_f32_e32 v170, v133
	v_add_f32_e32 v133, 1.0, v141
	v_rcp_f32_e32 v171, v133
	v_and_b32_e32 v133, 0xffff0000, v144
	v_lshlrev_b32_e32 v144, 16, v140
	v_and_b32_e32 v145, 0xffff0000, v140
	v_pk_mul_f32 v[140:141], v[122:123], v[132:133]
	v_lshlrev_b32_e32 v176, 16, v143
	v_pk_fma_f32 v[140:141], v[118:119], v[172:173], v[140:141]
	v_and_b32_e32 v177, 0xffff0000, v143
	v_pk_fma_f32 v[172:173], v[126:127], v[144:145], v[140:141]
	v_lshlrev_b32_e32 v174, 16, v131
	v_mul_f32_e32 v140, 0xbfb8aa3b, v172
	v_exp_f32_e32 v140, v140
	v_mul_f32_e32 v141, 0xbfb8aa3b, v173
	v_exp_f32_e32 v141, v141
	v_and_b32_e32 v175, 0xffff0000, v131
	v_add_f32_e32 v140, 1.0, v140
	v_pk_mul_f32 v[178:179], v[112:113], v[176:177]
	v_pk_mul_f32 v[170:171], v[152:153], v[170:171]
	v_rcp_f32_e32 v152, v140
	v_add_f32_e32 v153, 1.0, v141
	v_lshlrev_b32_e32 v140, 16, v139
	v_and_b32_e32 v141, 0xffff0000, v139
	v_pk_fma_f32 v[174:175], v[104:105], v[174:175], v[178:179]
	v_rcp_f32_e32 v153, v153
	v_pk_fma_f32 v[174:175], v[116:117], v[140:141], v[174:175]
	v_pk_mul_f32 v[184:185], v[124:125], v[150:151]
	v_mul_f32_e32 v131, 0xbfb8aa3b, v174
	v_exp_f32_e32 v131, v131
	v_mul_f32_e32 v139, 0xbfb8aa3b, v175
	v_exp_f32_e32 v139, v139
	v_pk_mul_f32 v[172:173], v[172:173], v[152:153]
	v_add_f32_e32 v131, 1.0, v131
	v_rcp_f32_e32 v178, v131
	v_add_f32_e32 v131, 1.0, v139
	v_rcp_f32_e32 v179, v131
	v_and_b32_e32 v131, 0xffff0000, v142
	v_lshlrev_b32_e32 v152, 16, v138
	v_and_b32_e32 v153, 0xffff0000, v138
	v_pk_mul_f32 v[174:175], v[174:175], v[178:179]
	v_lshlrev_b32_e32 v178, 16, v130
	v_and_b32_e32 v179, 0xffff0000, v130
	v_lshlrev_b32_e32 v130, 16, v142
	v_pk_mul_f32 v[138:139], v[110:111], v[130:131]
	v_pk_fma_f32 v[184:185], v[120:121], v[154:155], v[184:185]
	v_pk_fma_f32 v[138:139], v[102:103], v[178:179], v[138:139]
	v_lshlrev_b32_e32 v154, 16, v137
	v_pk_fma_f32 v[138:139], v[114:115], v[152:153], v[138:139]
	v_and_b32_e32 v155, 0xffff0000, v137
	v_mul_f32_e32 v142, 0xbfb8aa3b, v138
	v_mul_f32_e32 v143, 0xbfb8aa3b, v139
	v_exp_f32_e32 v142, v142
	v_exp_f32_e32 v143, v143
	v_pk_fma_f32 v[184:185], v[128:129], v[154:155], v[184:185]
	v_pk_mul_f32 v[192:193], v[112:113], v[140:141]
	v_mul_f32_e32 v137, 0xbfb8aa3b, v184
	v_exp_f32_e32 v137, v137
	v_mul_f32_e32 v186, 0xbfb8aa3b, v185
	v_add_f32_e32 v142, 1.0, v142
	v_add_f32_e32 v143, 1.0, v143
	v_exp_f32_e32 v187, v186
	v_rcp_f32_e32 v142, v142
	v_rcp_f32_e32 v143, v143
	v_add_f32_e32 v137, 1.0, v137
	v_rcp_f32_e32 v186, v137
	v_add_f32_e32 v137, 1.0, v187
	v_rcp_f32_e32 v187, v137
	v_pk_mul_f32 v[188:189], v[138:139], v[142:143]
	v_lshlrev_b32_e32 v142, 16, v136
	v_and_b32_e32 v143, 0xffff0000, v136
	v_pk_mul_f32 v[136:137], v[122:123], v[144:145]
	v_lshlrev_b32_e32 v138, 16, v135
	v_pk_fma_f32 v[132:133], v[118:119], v[132:133], v[136:137]
	v_and_b32_e32 v139, 0xffff0000, v135
	v_pk_fma_f32 v[132:133], v[126:127], v[142:143], v[132:133]
	v_pk_fma_f32 v[176:177], v[104:105], v[176:177], v[192:193]
	v_mul_f32_e32 v136, 0xbfb8aa3b, v132
	v_mul_f32_e32 v137, 0xbfb8aa3b, v133
	v_exp_f32_e32 v136, v136
	v_exp_f32_e32 v137, v137
	v_pk_fma_f32 v[176:177], v[116:117], v[138:139], v[176:177]
	v_pk_mul_f32 v[190:191], v[188:189], v[188:189]
	v_add_f32_e32 v136, 1.0, v136
	v_add_f32_e32 v137, 1.0, v137
	v_mul_f32_e32 v135, 0xbfb8aa3b, v176
	v_rcp_f32_e32 v136, v136
	v_rcp_f32_e32 v137, v137
	v_exp_f32_e32 v135, v135
	v_mul_f32_e32 v192, 0xbfb8aa3b, v177
	v_exp_f32_e32 v206, v192
	v_pk_mul_f32 v[192:193], v[132:133], v[136:137]
	v_add_f32_e32 v132, 1.0, v135
	v_lshlrev_b32_e32 v136, 16, v134
	v_and_b32_e32 v137, 0xffff0000, v134
	v_pk_mul_f32 v[134:135], v[110:111], v[152:153]
	v_add_f32_e32 v133, 1.0, v206
	v_pk_fma_f32 v[130:131], v[102:103], v[130:131], v[134:135]
	v_rcp_f32_e32 v132, v132
	v_pk_fma_f32 v[130:131], v[114:115], v[136:137], v[130:131]
	v_rcp_f32_e32 v133, v133
	v_mul_f32_e32 v134, 0xbfb8aa3b, v130
	v_mul_f32_e32 v135, 0xbfb8aa3b, v131
	v_exp_f32_e32 v134, v134
	v_exp_f32_e32 v135, v135
	v_pk_mul_f32 v[176:177], v[176:177], v[132:133]
	v_pk_mul_f32 v[178:179], v[174:175], v[174:175]
	v_add_f32_e32 v134, 1.0, v134
	v_add_f32_e32 v135, 1.0, v135
	v_rcp_f32_e32 v134, v134
	v_rcp_f32_e32 v135, v135
	v_pk_mul_f32 v[132:133], v[176:177], v[176:177]
	v_mov_b32_e32 v209, v190
	v_pk_mul_f32 v[182:183], v[172:173], v[172:173]
	v_pk_mul_f32 v[130:131], v[130:131], v[134:135]
	v_pk_mul_f32 v[206:207], v[192:193], v[192:193]
	v_pk_mul_f32 v[134:135], v[130:131], v[130:131]
	v_pk_mul_f32 v[184:185], v[184:185], v[186:187]
	v_mov_b32_e32 v208, v134
	v_mov_b32_e32 v190, v135
	v_pk_add_f32 v[134:135], v[208:209], v[190:191]
	v_mov_b32_e32 v190, v132
	v_mov_b32_e32 v191, v178
	v_pk_add_f32 v[134:135], v[190:191], v[134:135]
	v_mov_b32_e32 v178, v133
	v_pk_add_f32 v[132:133], v[178:179], v[134:135]
	v_mov_b32_e32 v134, v206
	v_mov_b32_e32 v135, v182
	v_pk_mul_f32 v[180:181], v[170:171], v[170:171]
	v_pk_mul_f32 v[186:187], v[184:185], v[184:185]
	v_pk_add_f32 v[132:133], v[134:135], v[132:133]
	v_mov_b32_e32 v182, v207
	v_pk_add_f32 v[132:133], v[182:183], v[132:133]
	v_mov_b32_e32 v134, v186
	v_mov_b32_e32 v135, v180
	v_pk_add_f32 v[132:133], v[134:135], v[132:133]
	v_mov_b32_e32 v180, v187
	v_pk_add_f32 v[132:133], v[180:181], v[132:133]
	s_mov_b32 s2, 0x358637bd
	v_addc_co_u32_e32 v35, vcc, 0, v35, vcc
	v_mov_b32_dpp v135, v133 quad_perm:[1,0,3,2] row_mask:0xf bank_mask:0xf bound_ctrl:1
	v_mov_b32_dpp v134, v132 quad_perm:[1,0,3,2] row_mask:0xf bank_mask:0xf bound_ctrl:1
	v_pk_add_f32 v[132:133], v[132:133], v[134:135]
	v_sub_u32_e32 v203, 63, v168
	v_lshl_add_u32 v0, v167, 1, v146
	v_mov_b32_dpp v135, v133 quad_perm:[2,3,0,1] row_mask:0xf bank_mask:0xf bound_ctrl:1
	v_mov_b32_dpp v134, v132 quad_perm:[2,3,0,1] row_mask:0xf bank_mask:0xf bound_ctrl:1
	v_pk_add_f32 v[132:133], v[132:133], v[134:135]
	global_load_dwordx4 v[42:45], v[32:33], off
	s_nop 0
	global_load_dwordx4 v[30:33], v[30:31], off offset:16
	v_mov_b32_dpp v135, v133 row_half_mirror row_mask:0xf bank_mask:0xf bound_ctrl:1
	v_mov_b32_dpp v134, v132 row_half_mirror row_mask:0xf bank_mask:0xf bound_ctrl:1
	v_pk_add_f32 v[132:133], v[132:133], v[134:135]
	global_load_dwordx4 v[46:49], v[34:35], off
	s_nop 0
	global_load_dwordx4 v[34:37], v[36:37], off offset:16
	v_mov_b32_dpp v135, v133 row_mirror row_mask:0xf bank_mask:0xf bound_ctrl:1
	v_mov_b32_dpp v134, v132 row_mirror row_mask:0xf bank_mask:0xf bound_ctrl:1
	v_pk_add_f32 v[132:133], v[132:133], v[134:135]
	v_and_b32_e32 v160, 63, v148
	v_pk_add_f32 v[134:135], v[132:133], s[2:3] op_sel_hi:[1,0]
	s_nop 0
	v_mul_f32_e32 v132, 0x4b800000, v135
	v_cmp_gt_f32_e32 vcc, s72, v135
	s_nop 1
	v_cndmask_b32_e32 v132, v135, v132, vcc
	v_rsq_f32_e32 v135, v132
	v_cndmask_b32_e64 v132, v203, v168, s[44:45]
	v_mad_u64_u32 v[132:133], s[0:1], v132, s14, v[0:1]
	v_mul_f32_e32 v133, 0x45800000, v135
	v_cndmask_b32_e32 v178, v135, v133, vcc
	v_mul_f32_e32 v133, 0x4b800000, v134
	v_cmp_gt_f32_e32 vcc, s72, v134
	v_pk_mul_f32 v[180:181], v[188:189], v[178:179] op_sel_hi:[1,0]
	v_pk_mul_f32 v[174:175], v[174:175], v[178:179] op_sel_hi:[1,0]
	v_cndmask_b32_e32 v133, v134, v133, vcc
	v_rsq_f32_e32 v133, v133
	v_pk_mul_f32 v[172:173], v[172:173], v[178:179] op_sel_hi:[1,0]
	v_pk_mul_f32 v[178:179], v[170:171], v[178:179] op_sel_hi:[1,0]
	v_cvt_pk_bf16_f32 v170, v180, v181
	v_mul_f32_e32 v134, 0x45800000, v133
	v_cvt_pk_bf16_f32 v171, v174, v175
	v_cvt_pk_bf16_f32 v172, v172, v173
	v_cvt_pk_bf16_f32 v173, v178, v179
	v_cndmask_b32_e32 v134, v133, v134, vcc
	ds_write_b128 v132, v[170:173]
	v_pk_mul_f32 v[130:131], v[130:131], v[134:135] op_sel_hi:[1,0]
	v_pk_mul_f32 v[172:173], v[176:177], v[134:135] op_sel_hi:[1,0]
	v_pk_mul_f32 v[174:175], v[192:193], v[134:135] op_sel_hi:[1,0]
	v_pk_mul_f32 v[134:135], v[184:185], v[134:135] op_sel_hi:[1,0]
	v_or_b32_e32 v133, 1, v168
	v_cvt_pk_bf16_f32 v171, v172, v173
	v_cvt_pk_bf16_f32 v173, v134, v135
	v_pk_mul_f32 v[134:135], v[124:125], v[154:155]
	v_sub_u32_e32 v170, 63, v133
	v_pk_fma_f32 v[134:135], v[120:121], v[150:151], v[134:135]
	v_lshlrev_b32_e32 v150, 16, v109
	v_and_b32_e32 v151, 0xffff0000, v109
	v_cndmask_b32_e64 v133, v170, v133, s[44:45]
	v_pk_fma_f32 v[134:135], v[128:129], v[150:151], v[134:135]
	v_pk_mul_f32 v[124:125], v[124:125], v[150:151]
	v_cvt_pk_bf16_f32 v170, v130, v131
	v_mad_u64_u32 v[130:131], s[0:1], v133, s14, v[0:1]
	v_mul_f32_e32 v109, 0xbfb8aa3b, v134
	v_pk_fma_f32 v[120:121], v[120:121], v[154:155], v[124:125]
	v_lshlrev_b32_e32 v124, 16, v101
	v_and_b32_e32 v125, 0xffff0000, v101
	v_exp_f32_e32 v109, v109
	v_mul_f32_e32 v131, 0xbfb8aa3b, v135
	v_pk_fma_f32 v[120:121], v[128:129], v[124:125], v[120:121]
	v_exp_f32_e32 v131, v131
	v_mul_f32_e32 v101, 0xbfb8aa3b, v120
	v_exp_f32_e32 v101, v101
	v_mul_f32_e32 v124, 0xbfb8aa3b, v121
	v_exp_f32_e32 v125, v124
	v_cvt_pk_bf16_f32 v172, v174, v175
	v_add_f32_e32 v109, 1.0, v109
	ds_write_b128 v130, v[170:173]
	v_rcp_f32_e32 v170, v109
	v_add_f32_e32 v109, 1.0, v131
	v_rcp_f32_e32 v171, v109
	v_lshlrev_b32_e32 v172, 16, v108
	v_and_b32_e32 v173, 0xffff0000, v108
	v_pk_mul_f32 v[108:109], v[122:123], v[142:143]
	v_add_f32_e32 v101, 1.0, v101
	v_pk_fma_f32 v[108:109], v[118:119], v[144:145], v[108:109]
	v_rcp_f32_e32 v124, v101
	v_add_f32_e32 v101, 1.0, v125
	v_pk_fma_f32 v[108:109], v[126:127], v[172:173], v[108:109]
	v_rcp_f32_e32 v125, v101
	v_mul_f32_e32 v131, 0xbfb8aa3b, v108
	v_exp_f32_e32 v131, v131
	v_mul_f32_e32 v133, 0xbfb8aa3b, v109
	v_exp_f32_e32 v133, v133
	v_pk_mul_f32 v[174:175], v[112:113], v[138:139]
	v_pk_mul_f32 v[134:135], v[134:135], v[170:171]
	v_lshlrev_b32_e32 v170, 16, v107
	v_and_b32_e32 v171, 0xffff0000, v107
	v_pk_fma_f32 v[140:141], v[104:105], v[140:141], v[174:175]
	v_pk_mul_f32 v[120:121], v[120:121], v[124:125]
	v_lshlrev_b32_e32 v124, 16, v100
	v_and_b32_e32 v125, 0xffff0000, v100
	v_pk_mul_f32 v[100:101], v[122:123], v[172:173]
	v_pk_fma_f32 v[140:141], v[116:117], v[170:171], v[140:141]
	v_pk_fma_f32 v[100:101], v[118:119], v[142:143], v[100:101]
	v_add_f32_e32 v131, 1.0, v131
	v_mul_f32_e32 v107, 0xbfb8aa3b, v140
	v_pk_fma_f32 v[100:101], v[126:127], v[124:125], v[100:101]
	v_rcp_f32_e32 v144, v131
	v_add_f32_e32 v131, 1.0, v133
	v_exp_f32_e32 v107, v107
	v_mul_f32_e32 v133, 0xbfb8aa3b, v141
	v_mul_f32_e32 v118, 0xbfb8aa3b, v100
	v_exp_f32_e32 v133, v133
	v_exp_f32_e32 v122, v118
	v_mul_f32_e32 v118, 0xbfb8aa3b, v101
	v_exp_f32_e32 v123, v118
	v_pk_mul_f32 v[112:113], v[112:113], v[170:171]
	v_lshlrev_b32_e32 v124, 16, v99
	v_and_b32_e32 v125, 0xffff0000, v99
	v_pk_fma_f32 v[104:105], v[104:105], v[138:139], v[112:113]
	v_add_f32_e32 v107, 1.0, v107
	v_pk_fma_f32 v[104:105], v[116:117], v[124:125], v[104:105]
	v_rcp_f32_e32 v174, v107
	v_add_f32_e32 v107, 1.0, v133
	v_mul_f32_e32 v99, 0xbfb8aa3b, v104
	v_rcp_f32_e32 v175, v107
	v_add_f32_e32 v122, 1.0, v122
	v_add_f32_e32 v123, 1.0, v123
	v_exp_f32_e32 v99, v99
	v_mul_f32_e32 v112, 0xbfb8aa3b, v105
	v_rcp_f32_e32 v122, v122
	v_rcp_f32_e32 v123, v123
	v_exp_f32_e32 v116, v112
	v_pk_mul_f32 v[140:141], v[140:141], v[174:175]
	v_lshlrev_b32_e32 v174, 16, v106
	v_and_b32_e32 v175, 0xffff0000, v106
	v_pk_mul_f32 v[106:107], v[110:111], v[136:137]
	v_add_f32_e32 v99, 1.0, v99
	v_pk_fma_f32 v[106:107], v[102:103], v[152:153], v[106:107]
	v_pk_mul_f32 v[112:113], v[100:101], v[122:123]
	v_rcp_f32_e32 v100, v99
	v_add_f32_e32 v101, 1.0, v116
	v_lshlrev_b32_e32 v116, 16, v98
	v_and_b32_e32 v117, 0xffff0000, v98
	v_pk_mul_f32 v[98:99], v[110:111], v[174:175]
	v_pk_fma_f32 v[106:107], v[114:115], v[174:175], v[106:107]
	v_pk_fma_f32 v[98:99], v[102:103], v[136:137], v[98:99]
	v_rcp_f32_e32 v145, v131
	v_mul_f32_e32 v131, 0xbfb8aa3b, v106
	v_pk_fma_f32 v[98:99], v[114:115], v[116:117], v[98:99]
	v_exp_f32_e32 v131, v131
	v_mul_f32_e32 v133, 0xbfb8aa3b, v107
	v_mul_f32_e32 v102, 0xbfb8aa3b, v98
	v_mul_f32_e32 v103, 0xbfb8aa3b, v99
	v_exp_f32_e32 v133, v133
	v_exp_f32_e32 v102, v102
	v_exp_f32_e32 v103, v103
	v_add_f32_e32 v131, 1.0, v131
	v_rcp_f32_e32 v178, v131
	v_add_f32_e32 v131, 1.0, v133
	v_add_f32_e32 v102, 1.0, v102
	v_add_f32_e32 v103, 1.0, v103
	v_rcp_f32_e32 v179, v131
	v_rcp_f32_e32 v102, v102
	v_rcp_f32_e32 v103, v103
	v_rcp_f32_e32 v101, v101
	v_pk_mul_f32 v[106:107], v[106:107], v[178:179]
	v_pk_mul_f32 v[152:153], v[140:141], v[140:141]
	v_pk_mul_f32 v[114:115], v[98:99], v[102:103]
	v_pk_mul_f32 v[128:129], v[106:107], v[106:107]
	v_pk_mul_f32 v[104:105], v[104:105], v[100:101]
	v_pk_mul_f32 v[98:99], v[114:115], v[114:115]
	v_pk_mul_f32 v[100:101], v[104:105], v[104:105]
	v_mov_b32_e32 v102, v98
	v_mov_b32_e32 v103, v128
	v_mov_b32_e32 v128, v99
	v_pk_mul_f32 v[108:109], v[108:109], v[144:145]
	v_pk_add_f32 v[98:99], v[102:103], v[128:129]
	v_mov_b32_e32 v102, v100
	v_mov_b32_e32 v103, v152
	v_pk_mul_f32 v[144:145], v[108:109], v[108:109]
	v_pk_mul_f32 v[110:111], v[112:113], v[112:113]
	v_pk_add_f32 v[98:99], v[102:103], v[98:99]
	v_mov_b32_e32 v152, v101
	v_pk_add_f32 v[98:99], v[152:153], v[98:99]
	v_mov_b32_e32 v100, v110
	v_mov_b32_e32 v101, v144
	v_pk_mul_f32 v[176:177], v[134:135], v[134:135]
	v_pk_mul_f32 v[118:119], v[120:121], v[120:121]
	v_pk_add_f32 v[98:99], v[100:101], v[98:99]
	v_mov_b32_e32 v144, v111
	v_pk_add_f32 v[98:99], v[144:145], v[98:99]
	v_mov_b32_e32 v100, v118
	v_mov_b32_e32 v101, v176
	v_pk_add_f32 v[98:99], v[100:101], v[98:99]
	v_mov_b32_e32 v176, v119
	v_pk_add_f32 v[98:99], v[176:177], v[98:99]
	v_or_b32_e32 v131, 2, v168
	v_sub_u32_e32 v133, 63, v131
	v_mov_b32_dpp v101, v99 quad_perm:[1,0,3,2] row_mask:0xf bank_mask:0xf bound_ctrl:1
	v_mov_b32_dpp v100, v98 quad_perm:[1,0,3,2] row_mask:0xf bank_mask:0xf bound_ctrl:1
	v_pk_add_f32 v[98:99], v[98:99], v[100:101]
	v_lshlrev_b32_e32 v118, 16, v89
	v_and_b32_e32 v119, 0xffff0000, v89
	v_mov_b32_dpp v101, v99 quad_perm:[2,3,0,1] row_mask:0xf bank_mask:0xf bound_ctrl:1
	v_mov_b32_dpp v100, v98 quad_perm:[2,3,0,1] row_mask:0xf bank_mask:0xf bound_ctrl:1
	v_pk_add_f32 v[98:99], v[98:99], v[100:101]
	s_nop 1
	v_mov_b32_dpp v101, v99 row_half_mirror row_mask:0xf bank_mask:0xf bound_ctrl:1
	v_mov_b32_dpp v100, v98 row_half_mirror row_mask:0xf bank_mask:0xf bound_ctrl:1
	v_pk_add_f32 v[98:99], v[98:99], v[100:101]
	s_nop 1
	v_mov_b32_dpp v101, v99 row_mirror row_mask:0xf bank_mask:0xf bound_ctrl:1
	v_mov_b32_dpp v100, v98 row_mirror row_mask:0xf bank_mask:0xf bound_ctrl:1
	v_pk_add_f32 v[98:99], v[98:99], v[100:101]
	s_nop 0
	v_pk_add_f32 v[100:101], v[98:99], s[2:3] op_sel_hi:[1,0]
	v_cndmask_b32_e64 v99, v133, v131, s[44:45]
	v_mul_f32_e32 v98, 0x4b800000, v101
	v_cmp_gt_f32_e32 vcc, s72, v101
	v_mad_u64_u32 v[102:103], s[0:1], v99, s14, v[0:1]
	s_nop 0
	v_cndmask_b32_e32 v98, v101, v98, vcc
	v_rsq_f32_e32 v98, v98
	v_mul_f32_e32 v101, 0x4b800000, v100
	v_and_b32_e32 v133, 0xffff0000, v54
	v_mul_f32_e32 v99, 0x45800000, v98
	v_cndmask_b32_e32 v98, v98, v99, vcc
	v_cmp_gt_f32_e32 vcc, s72, v100
	v_pk_mul_f32 v[106:107], v[106:107], v[98:99] op_sel_hi:[1,0]
	v_pk_mul_f32 v[110:111], v[140:141], v[98:99] op_sel_hi:[1,0]
	v_cndmask_b32_e32 v100, v100, v101, vcc
	v_rsq_f32_e32 v103, v100
	v_pk_mul_f32 v[108:109], v[108:109], v[98:99] op_sel_hi:[1,0]
	v_pk_mul_f32 v[116:117], v[134:135], v[98:99] op_sel_hi:[1,0]
	v_cvt_pk_bf16_f32 v98, v106, v107
	v_cvt_pk_bf16_f32 v99, v110, v111
	v_cvt_pk_bf16_f32 v100, v108, v109
	v_cvt_pk_bf16_f32 v101, v116, v117
	ds_write_b128 v102, v[98:101]
	v_mul_f32_e32 v98, 0x45800000, v103
	v_cndmask_b32_e32 v98, v103, v98, vcc
	v_pk_mul_f32 v[100:101], v[114:115], v[98:99] op_sel_hi:[1,0]
	v_pk_mul_f32 v[104:105], v[104:105], v[98:99] op_sel_hi:[1,0]
	v_pk_mul_f32 v[106:107], v[112:113], v[98:99] op_sel_hi:[1,0]
	v_pk_mul_f32 v[108:109], v[120:121], v[98:99] op_sel_hi:[1,0]
	v_or_b32_e32 v98, 3, v168
	v_sub_u32_e32 v99, 63, v98
	v_lshlrev_b32_e32 v110, 16, v97
	v_and_b32_e32 v111, 0xffff0000, v97
	v_cndmask_b32_e64 v103, v99, v98, s[44:45]
	v_cvt_pk_bf16_f32 v98, v100, v101
	v_cvt_pk_bf16_f32 v99, v104, v105
	v_lshlrev_b32_e32 v100, 16, v85
	v_and_b32_e32 v101, 0xffff0000, v85
	s_waitcnt vmcnt(8)
	v_pk_mul_f32 v[104:105], v[76:77], v[110:111]
	v_lshlrev_b32_e32 v116, 16, v84
	v_pk_fma_f32 v[100:101], v[72:73], v[100:101], v[104:105]
	v_lshlrev_b32_e32 v104, 16, v93
	v_and_b32_e32 v105, 0xffff0000, v93
	s_waitcnt vmcnt(6)
	v_pk_fma_f32 v[112:113], v[80:81], v[104:105], v[100:101]
	v_and_b32_e32 v117, 0xffff0000, v84
	v_mul_f32_e32 v85, 0xbfb8aa3b, v112
	v_exp_f32_e32 v85, v85
	v_mul_f32_e32 v93, 0xbfb8aa3b, v113
	v_exp_f32_e32 v93, v93
	v_lshlrev_b32_e32 v84, 16, v96
	v_add_f32_e32 v85, 1.0, v85
	v_rcp_f32_e32 v114, v85
	v_and_b32_e32 v85, 0xffff0000, v96
	v_cvt_pk_bf16_f32 v100, v106, v107
	v_add_f32_e32 v97, 1.0, v93
	v_lshlrev_b32_e32 v106, 16, v92
	v_and_b32_e32 v107, 0xffff0000, v92
	v_pk_mul_f32 v[92:93], v[74:75], v[84:85]
	v_rcp_f32_e32 v115, v97
	v_pk_fma_f32 v[92:93], v[70:71], v[116:117], v[92:93]
	v_lshlrev_b32_e32 v116, 16, v90
	v_pk_fma_f32 v[92:93], v[78:79], v[106:107], v[92:93]
	v_pk_mul_f32 v[120:121], v[112:113], v[114:115]
	v_mul_f32_e32 v96, 0xbfb8aa3b, v92
	v_mul_f32_e32 v101, 0xbfb8aa3b, v93
	v_exp_f32_e32 v96, v96
	v_exp_f32_e32 v101, v101
	v_lshlrev_b32_e32 v114, 16, v82
	v_and_b32_e32 v115, 0xffff0000, v82
	v_add_f32_e32 v96, 1.0, v96
	v_add_f32_e32 v97, 1.0, v101
	v_rcp_f32_e32 v96, v96
	v_rcp_f32_e32 v97, v97
	v_cvt_pk_bf16_f32 v101, v108, v109
	v_lshlrev_b32_e32 v108, 16, v91
	v_and_b32_e32 v109, 0xffff0000, v91
	v_pk_mul_f32 v[124:125], v[92:93], v[96:97]
	v_lshlrev_b32_e32 v96, 16, v95
	v_and_b32_e32 v97, 0xffff0000, v95
	v_lshlrev_b32_e32 v92, 16, v83
	v_and_b32_e32 v93, 0xffff0000, v83
	v_pk_mul_f32 v[112:113], v[64:65], v[96:97]
	v_lshlrev_b32_e32 v82, 16, v94
	v_pk_fma_f32 v[92:93], v[60:61], v[92:93], v[112:113]
	v_and_b32_e32 v117, 0xffff0000, v90
	v_pk_fma_f32 v[92:93], v[68:69], v[108:109], v[92:93]
	v_pk_mul_f32 v[136:137], v[64:65], v[108:109]
	v_mul_f32_e32 v83, 0xbfb8aa3b, v92
	v_exp_f32_e32 v83, v83
	v_mul_f32_e32 v91, 0xbfb8aa3b, v93
	v_exp_f32_e32 v91, v91
	v_pk_fma_f32 v[96:97], v[60:61], v[96:97], v[136:137]
	v_add_f32_e32 v83, 1.0, v83
	v_rcp_f32_e32 v112, v83
	v_add_f32_e32 v83, 1.0, v91
	v_rcp_f32_e32 v113, v83
	v_and_b32_e32 v83, 0xffff0000, v94
	v_pk_mul_f32 v[90:91], v[62:63], v[82:83]
	v_pk_mul_f32 v[126:127], v[124:125], v[124:125]
	v_pk_fma_f32 v[90:91], v[58:59], v[114:115], v[90:91]
	v_pk_mul_f32 v[122:123], v[120:121], v[120:121]
	v_pk_fma_f32 v[90:91], v[66:67], v[116:117], v[90:91]
	s_nop 0
	v_mul_f32_e32 v94, 0xbfb8aa3b, v90
	v_exp_f32_e32 v114, v94
	v_mul_f32_e32 v94, 0xbfb8aa3b, v91
	v_exp_f32_e32 v115, v94
	v_pk_mul_f32 v[94:95], v[92:93], v[112:113]
	v_pk_mul_f32 v[112:113], v[76:77], v[104:105]
	v_add_f32_e32 v92, 1.0, v114
	v_pk_fma_f32 v[110:111], v[72:73], v[110:111], v[112:113]
	v_add_f32_e32 v93, 1.0, v115
	v_pk_fma_f32 v[110:111], v[80:81], v[118:119], v[110:111]
	v_lshlrev_b32_e32 v114, 16, v88
	v_mul_f32_e32 v89, 0xbfb8aa3b, v110
	v_exp_f32_e32 v89, v89
	v_mul_f32_e32 v112, 0xbfb8aa3b, v111
	v_exp_f32_e32 v113, v112
	v_and_b32_e32 v115, 0xffff0000, v88
	v_add_f32_e32 v89, 1.0, v89
	v_rcp_f32_e32 v112, v89
	v_add_f32_e32 v89, 1.0, v113
	v_rcp_f32_e32 v113, v89
	v_pk_mul_f32 v[88:89], v[74:75], v[106:107]
	v_rcp_f32_e32 v92, v92
	v_pk_fma_f32 v[84:85], v[70:71], v[84:85], v[88:89]
	v_pk_mul_f32 v[134:135], v[110:111], v[112:113]
	v_pk_fma_f32 v[84:85], v[78:79], v[114:115], v[84:85]
	v_lshlrev_b32_e32 v112, 16, v87
	v_mul_f32_e32 v88, 0xbfb8aa3b, v84
	v_exp_f32_e32 v110, v88
	v_mul_f32_e32 v88, 0xbfb8aa3b, v85
	v_exp_f32_e32 v111, v88
	v_and_b32_e32 v113, 0xffff0000, v87
	v_pk_fma_f32 v[96:97], v[68:69], v[112:113], v[96:97]
	v_add_f32_e32 v110, 1.0, v110
	v_add_f32_e32 v111, 1.0, v111
	v_mul_f32_e32 v87, 0xbfb8aa3b, v96
	v_rcp_f32_e32 v110, v110
	v_rcp_f32_e32 v111, v111
	v_exp_f32_e32 v87, v87
	v_mul_f32_e32 v131, 0xbfb8aa3b, v97
	v_exp_f32_e32 v131, v131
	v_pk_mul_f32 v[136:137], v[84:85], v[110:111]
	v_add_f32_e32 v84, 1.0, v87
	v_lshlrev_b32_e32 v110, 16, v86
	v_and_b32_e32 v111, 0xffff0000, v86
	v_pk_mul_f32 v[86:87], v[62:63], v[116:117]
	v_rcp_f32_e32 v93, v93
	v_pk_fma_f32 v[82:83], v[58:59], v[82:83], v[86:87]
	v_add_f32_e32 v85, 1.0, v131
	v_pk_fma_f32 v[82:83], v[66:67], v[110:111], v[82:83]
	v_rcp_f32_e32 v84, v84
	v_mul_f32_e32 v86, 0xbfb8aa3b, v82
	v_mul_f32_e32 v87, 0xbfb8aa3b, v83
	v_exp_f32_e32 v86, v86
	v_exp_f32_e32 v87, v87
	v_rcp_f32_e32 v85, v85
	v_pk_mul_f32 v[90:91], v[90:91], v[92:93]
	v_add_f32_e32 v86, 1.0, v86
	v_add_f32_e32 v87, 1.0, v87
	v_rcp_f32_e32 v86, v86
	v_rcp_f32_e32 v87, v87
	v_pk_mul_f32 v[92:93], v[90:91], v[90:91]
	v_pk_mul_f32 v[140:141], v[96:97], v[84:85]
	v_pk_mul_f32 v[128:129], v[94:95], v[94:95]
	v_pk_mul_f32 v[86:87], v[82:83], v[86:87]
	v_pk_mul_f32 v[84:85], v[140:141], v[140:141]
	v_pk_mul_f32 v[82:83], v[86:87], v[86:87]
	v_mov_b32_e32 v97, v92
	v_mov_b32_e32 v96, v82
	v_mov_b32_e32 v92, v83
	v_pk_add_f32 v[82:83], v[96:97], v[92:93]
	v_mov_b32_e32 v92, v84
	v_mov_b32_e32 v93, v128
	v_pk_mul_f32 v[138:139], v[136:137], v[136:137]
	v_pk_add_f32 v[82:83], v[92:93], v[82:83]
	v_mov_b32_e32 v128, v85
	v_pk_add_f32 v[82:83], v[128:129], v[82:83]
	v_mov_b32_e32 v84, v138
	v_mov_b32_e32 v85, v126
	v_pk_mul_f32 v[88:89], v[134:135], v[134:135]
	v_pk_add_f32 v[82:83], v[84:85], v[82:83]
	v_mov_b32_e32 v126, v139
	v_pk_add_f32 v[82:83], v[126:127], v[82:83]
	v_mov_b32_e32 v84, v88
	v_mov_b32_e32 v85, v122
	v_pk_add_f32 v[82:83], v[84:85], v[82:83]
	v_mov_b32_e32 v122, v89
	v_pk_add_f32 v[82:83], v[122:123], v[82:83]
	v_mad_u64_u32 v[96:97], s[0:1], v103, s14, v[0:1]
	s_nop 0
	v_mov_b32_dpp v85, v83 quad_perm:[1,0,3,2] row_mask:0xf bank_mask:0xf bound_ctrl:1
	v_mov_b32_dpp v84, v82 quad_perm:[1,0,3,2] row_mask:0xf bank_mask:0xf bound_ctrl:1
	v_pk_add_f32 v[82:83], v[82:83], v[84:85]
	ds_write_b128 v96, v[98:101]
	v_pk_mul_f32 v[126:127], v[64:65], v[112:113]
	v_mov_b32_dpp v85, v83 quad_perm:[2,3,0,1] row_mask:0xf bank_mask:0xf bound_ctrl:1
	v_mov_b32_dpp v84, v82 quad_perm:[2,3,0,1] row_mask:0xf bank_mask:0xf bound_ctrl:1
	v_pk_add_f32 v[82:83], v[82:83], v[84:85]
	v_pk_fma_f32 v[108:109], v[60:61], v[108:109], v[126:127]
	s_movk_i32 s0, 0x48
	v_mov_b32_dpp v85, v83 row_half_mirror row_mask:0xf bank_mask:0xf bound_ctrl:1
	v_mov_b32_dpp v84, v82 row_half_mirror row_mask:0xf bank_mask:0xf bound_ctrl:1
	v_pk_add_f32 v[82:83], v[82:83], v[84:85]
	s_nop 1
	v_mov_b32_dpp v85, v83 row_mirror row_mask:0xf bank_mask:0xf bound_ctrl:1
	v_mov_b32_dpp v84, v82 row_mirror row_mask:0xf bank_mask:0xf bound_ctrl:1
	v_pk_add_f32 v[82:83], v[82:83], v[84:85]
	s_nop 0
	v_pk_add_f32 v[122:123], v[82:83], s[2:3] op_sel_hi:[1,0]
	s_nop 0
	v_mul_f32_e32 v82, 0x4b800000, v123
	v_cmp_gt_f32_e32 vcc, s72, v123
	s_nop 1
	v_cndmask_b32_e32 v82, v123, v82, vcc
	v_rsq_f32_e32 v82, v82
	s_nop 0
	v_mul_f32_e32 v0, 0x45800000, v82
	v_cndmask_b32_e32 v0, v82, v0, vcc
	v_pk_mul_f32 v[92:93], v[90:91], v[0:1] op_sel_hi:[1,0]
	v_pk_mul_f32 v[88:89], v[94:95], v[0:1] op_sel_hi:[1,0]
	v_pk_mul_f32 v[84:85], v[124:125], v[0:1] op_sel_hi:[1,0]
	v_pk_mul_f32 v[82:83], v[120:121], v[0:1] op_sel_hi:[1,0]
	v_mul_f32_e32 v0, 0x4b800000, v122
	v_cmp_gt_f32_e32 vcc, s72, v122
	v_cvt_pk_bf16_f32 v98, v92, v93
	v_cvt_pk_bf16_f32 v99, v88, v89
	v_cndmask_b32_e32 v0, v122, v0, vcc
	v_rsq_f32_e32 v0, v0
	v_cvt_pk_bf16_f32 v100, v84, v85
	v_cvt_pk_bf16_f32 v101, v82, v83
	ds_write_b128 v132, v[98:101] offset:17408
	v_pk_mul_f32 v[100:101], v[76:77], v[118:119]
	v_mul_f32_e32 v90, 0x45800000, v0
	v_pk_fma_f32 v[100:101], v[72:73], v[104:105], v[100:101]
	v_lshlrev_b32_e32 v120, 16, v57
	v_and_b32_e32 v121, 0xffff0000, v57
	v_cndmask_b32_e32 v0, v0, v90, vcc
	v_pk_fma_f32 v[100:101], v[80:81], v[120:121], v[100:101]
	v_pk_mul_f32 v[98:99], v[86:87], v[0:1] op_sel_hi:[1,0]
	v_pk_mul_f32 v[94:95], v[140:141], v[0:1] op_sel_hi:[1,0]
	v_pk_mul_f32 v[90:91], v[136:137], v[0:1] op_sel_hi:[1,0]
	v_pk_mul_f32 v[86:87], v[134:135], v[0:1] op_sel_hi:[1,0]
	v_mul_f32_e32 v0, 0xbfb8aa3b, v100
	v_exp_f32_e32 v0, v0
	v_mul_f32_e32 v57, 0xbfb8aa3b, v101
	v_exp_f32_e32 v57, v57
	v_lshlrev_b32_e32 v124, 16, v56
	v_add_f32_e32 v0, 1.0, v0
	v_rcp_f32_e32 v122, v0
	v_add_f32_e32 v0, 1.0, v57
	v_and_b32_e32 v125, 0xffff0000, v56
	v_pk_mul_f32 v[56:57], v[74:75], v[114:115]
	v_rcp_f32_e32 v123, v0
	v_pk_fma_f32 v[56:57], v[70:71], v[106:107], v[56:57]
	v_lshlrev_b32_e32 v132, 16, v54
	v_pk_fma_f32 v[56:57], v[78:79], v[124:125], v[56:57]
	v_pk_mul_f32 v[76:77], v[76:77], v[120:121]
	v_mul_f32_e32 v97, 0xbfb8aa3b, v56
	v_exp_f32_e32 v97, v97
	v_mul_f32_e32 v103, 0xbfb8aa3b, v57
	v_exp_f32_e32 v103, v103
	v_pk_fma_f32 v[72:73], v[72:73], v[118:119], v[76:77]
	v_add_f32_e32 v0, 1.0, v97
	v_rcp_f32_e32 v106, v0
	v_add_f32_e32 v0, 1.0, v103
	v_rcp_f32_e32 v107, v0
	v_lshlrev_b32_e32 v76, 16, v53
	v_and_b32_e32 v77, 0xffff0000, v53
	v_pk_fma_f32 v[72:73], v[80:81], v[76:77], v[72:73]
	v_pk_mul_f32 v[56:57], v[56:57], v[106:107]
	v_lshlrev_b32_e32 v106, 16, v55
	v_and_b32_e32 v107, 0xffff0000, v55
	v_pk_fma_f32 v[108:109], v[68:69], v[106:107], v[108:109]
	v_mul_f32_e32 v53, 0xbfb8aa3b, v72
	v_mul_f32_e32 v0, 0xbfb8aa3b, v108
	v_exp_f32_e32 v0, v0
	v_mul_f32_e32 v55, 0xbfb8aa3b, v109
	v_exp_f32_e32 v55, v55
	v_exp_f32_e32 v53, v53
	v_add_f32_e32 v0, 1.0, v0
	v_rcp_f32_e32 v128, v0
	v_add_f32_e32 v0, 1.0, v55
	v_pk_mul_f32 v[54:55], v[62:63], v[110:111]
	v_rcp_f32_e32 v129, v0
	v_pk_fma_f32 v[54:55], v[58:59], v[116:117], v[54:55]
	v_mul_f32_e32 v76, 0xbfb8aa3b, v73
	v_pk_fma_f32 v[54:55], v[66:67], v[132:133], v[54:55]
	v_exp_f32_e32 v77, v76
	v_mul_f32_e32 v0, 0xbfb8aa3b, v54
	v_exp_f32_e32 v0, v0
	v_mul_f32_e32 v97, 0xbfb8aa3b, v55
	v_exp_f32_e32 v97, v97
	v_pk_mul_f32 v[64:65], v[64:65], v[106:107]
	v_add_f32_e32 v0, 1.0, v0
	v_rcp_f32_e32 v116, v0
	v_add_f32_e32 v0, 1.0, v97
	v_rcp_f32_e32 v117, v0
	v_add_f32_e32 v0, 1.0, v53
	v_rcp_f32_e32 v76, v0
	v_add_f32_e32 v0, 1.0, v77
	v_rcp_f32_e32 v77, v0
	v_pk_fma_f32 v[60:61], v[60:61], v[112:113], v[64:65]
	v_pk_mul_f32 v[54:55], v[54:55], v[116:117]
	v_pk_mul_f32 v[108:109], v[108:109], v[128:129]
	v_pk_mul_f32 v[72:73], v[72:73], v[76:77]
	v_lshlrev_b32_e32 v76, 16, v52
	v_and_b32_e32 v77, 0xffff0000, v52
	v_pk_mul_f32 v[52:53], v[74:75], v[124:125]
	v_pk_mul_f32 v[116:117], v[54:55], v[54:55]
	v_pk_fma_f32 v[52:53], v[70:71], v[114:115], v[52:53]
	v_pk_mul_f32 v[80:81], v[108:109], v[108:109]
	v_pk_fma_f32 v[52:53], v[78:79], v[76:77], v[52:53]
	v_lshlrev_b32_e32 v76, 16, v51
	v_mul_f32_e32 v0, 0xbfb8aa3b, v52
	v_exp_f32_e32 v0, v0
	v_mul_f32_e32 v70, 0xbfb8aa3b, v53
	v_exp_f32_e32 v75, v70
	v_and_b32_e32 v77, 0xffff0000, v51
	v_add_f32_e32 v0, 1.0, v0
	v_rcp_f32_e32 v74, v0
	v_add_f32_e32 v0, 1.0, v75
	v_pk_fma_f32 v[60:61], v[68:69], v[76:77], v[60:61]
	v_rcp_f32_e32 v75, v0
	v_mul_f32_e32 v0, 0xbfb8aa3b, v60
	v_exp_f32_e32 v0, v0
	v_mul_f32_e32 v51, 0xbfb8aa3b, v61
	v_exp_f32_e32 v51, v51
	v_pk_mul_f32 v[64:65], v[52:53], v[74:75]
	v_add_f32_e32 v0, 1.0, v0
	v_rcp_f32_e32 v52, v0
	v_add_f32_e32 v0, 1.0, v51
	v_lshlrev_b32_e32 v68, 16, v50
	v_and_b32_e32 v69, 0xffff0000, v50
	v_pk_mul_f32 v[50:51], v[62:63], v[132:133]
	v_pk_mul_f32 v[126:127], v[56:57], v[56:57]
	v_pk_fma_f32 v[50:51], v[58:59], v[110:111], v[50:51]
	v_pk_mul_f32 v[62:63], v[64:65], v[64:65]
	v_pk_fma_f32 v[50:51], v[66:67], v[68:69], v[50:51]
	v_mov_b32_e32 v67, v116
	v_mul_f32_e32 v53, 0xbfb8aa3b, v50
	v_exp_f32_e32 v58, v53
	v_mul_f32_e32 v53, 0xbfb8aa3b, v51
	v_exp_f32_e32 v59, v53
	v_rcp_f32_e32 v53, v0
	v_add_f32_e32 v0, 1.0, v58
	v_rcp_f32_e32 v58, v0
	v_add_f32_e32 v0, 1.0, v59
	v_rcp_f32_e32 v59, v0
	v_pk_mul_f32 v[60:61], v[60:61], v[52:53]
	v_pk_mul_f32 v[100:101], v[100:101], v[122:123]
	v_pk_mul_f32 v[52:53], v[60:61], v[60:61]
	v_pk_mul_f32 v[58:59], v[50:51], v[58:59]
	v_pk_mul_f32 v[122:123], v[100:101], v[100:101]
	v_pk_mul_f32 v[50:51], v[58:59], v[58:59]
	v_pk_mul_f32 v[70:71], v[72:73], v[72:73]
	v_mov_b32_e32 v66, v50
	v_mov_b32_e32 v116, v51
	v_pk_add_f32 v[50:51], v[66:67], v[116:117]
	v_mov_b32_e32 v66, v52
	v_mov_b32_e32 v67, v80
	v_pk_add_f32 v[50:51], v[66:67], v[50:51]
	v_mov_b32_e32 v80, v53
	v_pk_add_f32 v[50:51], v[80:81], v[50:51]
	v_mov_b32_e32 v52, v62
	v_mov_b32_e32 v53, v126
	v_pk_add_f32 v[50:51], v[52:53], v[50:51]
	v_mov_b32_e32 v126, v63
	v_pk_add_f32 v[50:51], v[126:127], v[50:51]
	v_mov_b32_e32 v52, v70
	v_mov_b32_e32 v53, v122
	v_pk_add_f32 v[50:51], v[52:53], v[50:51]
	v_mov_b32_e32 v122, v71
	v_pk_add_f32 v[50:51], v[122:123], v[50:51]
	v_cvt_pk_bf16_f32 v104, v98, v99
	v_cvt_pk_bf16_f32 v105, v94, v95
	v_mov_b32_dpp v53, v51 quad_perm:[1,0,3,2] row_mask:0xf bank_mask:0xf bound_ctrl:1
	v_mov_b32_dpp v52, v50 quad_perm:[1,0,3,2] row_mask:0xf bank_mask:0xf bound_ctrl:1
	v_pk_add_f32 v[50:51], v[50:51], v[52:53]
	v_cvt_pk_bf16_f32 v106, v90, v91
	v_cvt_pk_bf16_f32 v107, v86, v87
	v_mov_b32_dpp v53, v51 quad_perm:[2,3,0,1] row_mask:0xf bank_mask:0xf bound_ctrl:1
	v_mov_b32_dpp v52, v50 quad_perm:[2,3,0,1] row_mask:0xf bank_mask:0xf bound_ctrl:1
	v_pk_add_f32 v[50:51], v[50:51], v[52:53]
	ds_write_b128 v130, v[104:107] offset:17408
	s_nop 0
	v_mov_b32_dpp v53, v51 row_half_mirror row_mask:0xf bank_mask:0xf bound_ctrl:1
	v_mov_b32_dpp v52, v50 row_half_mirror row_mask:0xf bank_mask:0xf bound_ctrl:1
	v_pk_add_f32 v[50:51], v[50:51], v[52:53]
	s_nop 1
	v_mov_b32_dpp v53, v51 row_mirror row_mask:0xf bank_mask:0xf bound_ctrl:1
	v_mov_b32_dpp v52, v50 row_mirror row_mask:0xf bank_mask:0xf bound_ctrl:1
	v_pk_add_f32 v[50:51], v[50:51], v[52:53]
	s_nop 0
	v_pk_add_f32 v[52:53], v[50:51], s[2:3] op_sel_hi:[1,0]
	s_nop 0
	v_mul_f32_e32 v0, 0x4b800000, v53
	v_cmp_gt_f32_e32 vcc, s72, v53
	s_nop 1
	v_cndmask_b32_e32 v0, v53, v0, vcc
	v_rsq_f32_e32 v0, v0
	s_nop 0
	v_mul_f32_e32 v50, 0x45800000, v0
	v_cndmask_b32_e32 v0, v0, v50, vcc
	v_pk_mul_f32 v[54:55], v[54:55], v[0:1] op_sel_hi:[1,0]
	v_pk_mul_f32 v[62:63], v[108:109], v[0:1] op_sel_hi:[1,0]
	v_pk_mul_f32 v[56:57], v[56:57], v[0:1] op_sel_hi:[1,0]
	v_pk_mul_f32 v[66:67], v[100:101], v[0:1] op_sel_hi:[1,0]
	v_mul_f32_e32 v0, 0x4b800000, v52
	v_cmp_gt_f32_e32 vcc, s72, v52
	v_cvt_pk_bf16_f32 v50, v54, v55
	v_cvt_pk_bf16_f32 v51, v62, v63
	v_cndmask_b32_e32 v0, v52, v0, vcc
	v_rsq_f32_e32 v0, v0
	v_cvt_pk_bf16_f32 v52, v56, v57
	v_cvt_pk_bf16_f32 v53, v66, v67
	ds_write_b128 v102, v[50:53] offset:17408
	v_mul_f32_e32 v50, 0x45800000, v0
	v_cndmask_b32_e32 v0, v0, v50, vcc
	v_pk_mul_f32 v[58:59], v[58:59], v[0:1] op_sel_hi:[1,0]
	v_pk_mul_f32 v[60:61], v[60:61], v[0:1] op_sel_hi:[1,0]
	v_pk_mul_f32 v[64:65], v[64:65], v[0:1] op_sel_hi:[1,0]
	v_pk_mul_f32 v[68:69], v[72:73], v[0:1] op_sel_hi:[1,0]
	v_cvt_pk_bf16_f32 v50, v58, v59
	v_cvt_pk_bf16_f32 v51, v60, v61
	v_cvt_pk_bf16_f32 v52, v64, v65
	v_cvt_pk_bf16_f32 v53, v68, v69
	ds_write_b128 v96, v[50:53] offset:17408
	v_cndmask_b32_e64 v0, v58, v92, s[44:45]
	v_cndmask_b32_e64 v50, v54, v98, s[44:45]
	v_cndmask_b32_e64 v51, v98, v54, s[44:45]
	v_cndmask_b32_e64 v52, v92, v58, s[44:45]
	v_cvt_pk_bf16_f32 v50, v0, v50
	v_mad_u32_u24 v0, v167, s0, v169
	v_cvt_pk_bf16_f32 v51, v51, v52
	v_lshl_add_u32 v0, v0, 1, v146
	v_cndmask_b32_e64 v52, v59, v93, s[44:45]
	v_cndmask_b32_e64 v53, v55, v99, s[44:45]
	v_cndmask_b32_e64 v54, v99, v55, s[44:45]
	v_cndmask_b32_e64 v55, v93, v59, s[44:45]
	v_cvt_pk_bf16_f32 v52, v52, v53
	v_cvt_pk_bf16_f32 v53, v54, v55
	v_add_u32_e32 v70, 0x8800, v0
	ds_write2_b64 v70, v[50:51], v[52:53] offset1:18
	v_cndmask_b32_e64 v50, v60, v88, s[44:45]
	v_cndmask_b32_e64 v51, v62, v94, s[44:45]
	v_cndmask_b32_e64 v52, v94, v62, s[44:45]
	v_cndmask_b32_e64 v53, v88, v60, s[44:45]
	v_cvt_pk_bf16_f32 v50, v50, v51
	v_cvt_pk_bf16_f32 v51, v52, v53
	v_cndmask_b32_e64 v52, v61, v89, s[44:45]
	v_cndmask_b32_e64 v53, v63, v95, s[44:45]
	v_cndmask_b32_e64 v54, v95, v63, s[44:45]
	v_cndmask_b32_e64 v55, v89, v61, s[44:45]
	v_cvt_pk_bf16_f32 v52, v52, v53
	v_cvt_pk_bf16_f32 v53, v54, v55
	ds_write2_b64 v70, v[50:51], v[52:53] offset0:36 offset1:54
	v_cndmask_b32_e64 v50, v64, v84, s[44:45]
	v_cndmask_b32_e64 v51, v56, v90, s[44:45]
	v_cndmask_b32_e64 v52, v90, v56, s[44:45]
	v_cndmask_b32_e64 v53, v84, v64, s[44:45]
	v_cvt_pk_bf16_f32 v50, v50, v51
	v_cvt_pk_bf16_f32 v51, v52, v53
	v_cndmask_b32_e64 v52, v65, v85, s[44:45]
	v_cndmask_b32_e64 v53, v57, v91, s[44:45]
	v_cndmask_b32_e64 v54, v91, v57, s[44:45]
	v_cndmask_b32_e64 v55, v85, v65, s[44:45]
	v_cvt_pk_bf16_f32 v52, v52, v53
	v_cvt_pk_bf16_f32 v53, v54, v55
	v_lshlrev_b32_e32 v54, 16, v10
	v_lshlrev_b32_e32 v56, 16, v6
	v_mov_b32_e32 v57, v54
	v_lshlrev_b32_e32 v55, 16, v2
	v_mov_b32_e32 v58, v56
	s_waitcnt vmcnt(3)
	v_pk_mul_f32 v[56:57], v[42:43], v[56:57] op_sel_hi:[0,1]
	ds_write2_b64 v70, v[50:51], v[52:53] offset0:72 offset1:90
	v_cndmask_b32_e64 v50, v68, v82, s[44:45]
	v_cndmask_b32_e64 v51, v66, v86, s[44:45]
	v_cndmask_b32_e64 v52, v86, v66, s[44:45]
	v_cndmask_b32_e64 v53, v82, v68, s[44:45]
	v_lshlrev_b32_e32 v59, 16, v18
	v_pk_fma_f32 v[54:55], v[38:39], v[54:55], v[56:57] op_sel_hi:[0,1,1]
	v_cvt_pk_bf16_f32 v50, v50, v51
	v_cvt_pk_bf16_f32 v51, v52, v53
	v_cndmask_b32_e64 v52, v69, v83, s[44:45]
	v_cndmask_b32_e64 v53, v67, v87, s[44:45]
	s_waitcnt vmcnt(1)
	v_pk_fma_f32 v[54:55], v[46:47], v[58:59], v[54:55] op_sel:[0,1,0] op_sel_hi:[0,0,1]
	v_cvt_pk_bf16_f32 v52, v52, v53
	v_mul_f32_e32 v53, 0xbfb8aa3b, v55
	v_exp_f32_e32 v53, v53
	v_mul_f32_e32 v56, 0xbfb8aa3b, v54
	v_exp_f32_e32 v56, v56
	v_lshlrev_b32_e32 v61, 16, v14
	v_mov_b32_e32 v60, v59
	v_add_f32_e32 v53, 1.0, v53
	v_rcp_f32_e32 v63, v53
	v_add_f32_e32 v53, 1.0, v56
	v_mov_b32_e32 v56, v61
	v_pk_mul_f32 v[60:61], v[42:43], v[60:61] op_sel_hi:[0,1]
	v_lshlrev_b32_e32 v57, 16, v22
	v_pk_fma_f32 v[58:59], v[38:39], v[58:59], v[60:61] op_sel_hi:[0,1,1]
	v_pk_fma_f32 v[56:57], v[46:47], v[56:57], v[58:59] op_sel_hi:[0,1,1]
	v_mul_f32_e32 v58, 0xbfb8aa3b, v56
	v_exp_f32_e32 v58, v58
	v_mul_f32_e32 v59, 0xbfb8aa3b, v57
	v_exp_f32_e32 v59, v59
	v_rcp_f32_e32 v62, v53
	v_add_f32_e32 v53, 1.0, v58
	v_rcp_f32_e32 v58, v53
	v_add_f32_e32 v53, 1.0, v59
	v_rcp_f32_e32 v59, v53
	v_cndmask_b32_e64 v64, v87, v67, s[44:45]
	v_cndmask_b32_e64 v65, v83, v69, s[44:45]
	v_cvt_pk_bf16_f32 v53, v64, v65
	ds_write2_b64 v70, v[50:51], v[52:53] offset0:108 offset1:126
	v_pk_mul_f32 v[50:51], v[54:55], v[62:63]
	v_pk_mul_f32 v[52:53], v[56:57], v[58:59]
	v_and_b32_e32 v55, 0xffff0000, v18
	v_cndmask_b32_e64 v61, v52, v50, s[44:45]
	v_cndmask_b32_e64 v63, v50, v52, s[44:45]
	v_and_b32_e32 v50, 0xffff0000, v10
	v_cndmask_b32_e64 v60, v53, v51, s[44:45]
	v_cndmask_b32_e64 v62, v51, v53, s[44:45]
	v_and_b32_e32 v52, 0xffff0000, v6
	v_mov_b32_e32 v53, v50
	v_and_b32_e32 v51, 0xffff0000, v2
	v_mov_b32_e32 v54, v52
	v_pk_mul_f32 v[52:53], v[42:43], v[52:53] op_sel:[1,0]
	v_and_b32_e32 v57, 0xffff0000, v14
	v_pk_fma_f32 v[50:51], v[38:39], v[50:51], v[52:53] op_sel:[1,0,0]
	v_mov_b32_e32 v56, v55
	v_pk_fma_f32 v[50:51], v[46:47], v[54:55], v[50:51] op_sel:[1,1,0] op_sel_hi:[1,0,1]
	v_pk_mul_f32 v[42:43], v[42:43], v[56:57] op_sel:[1,0]
	v_mul_f32_e32 v2, 0xbfb8aa3b, v51
	v_exp_f32_e32 v2, v2
	v_mul_f32_e32 v6, 0xbfb8aa3b, v50
	v_exp_f32_e32 v6, v6
	v_and_b32_e32 v53, 0xffff0000, v22
	v_mov_b32_e32 v52, v57
	v_pk_fma_f32 v[38:39], v[38:39], v[54:55], v[42:43] op_sel:[1,0,0]
	v_add_f32_e32 v2, 1.0, v2
	v_pk_fma_f32 v[38:39], v[46:47], v[52:53], v[38:39] op_sel:[1,0,0]
	v_rcp_f32_e32 v59, v2
	v_add_f32_e32 v2, 1.0, v6
	v_mul_f32_e32 v6, 0xbfb8aa3b, v38
	v_exp_f32_e32 v6, v6
	v_mul_f32_e32 v10, 0xbfb8aa3b, v39
	v_exp_f32_e32 v10, v10
	v_rcp_f32_e32 v58, v2
	v_add_f32_e32 v2, 1.0, v6
	v_rcp_f32_e32 v42, v2
	v_add_f32_e32 v2, 1.0, v10
	v_rcp_f32_e32 v43, v2
	v_pk_mul_f32 v[50:51], v[50:51], v[58:59]
	v_lshlrev_b32_e32 v53, 16, v19
	v_lshlrev_b32_e32 v55, 16, v15
	v_pk_mul_f32 v[38:39], v[38:39], v[42:43]
	v_lshlrev_b32_e32 v42, 16, v11
	v_cndmask_b32_e64 v2, v39, v51, s[44:45]
	v_cndmask_b32_e64 v6, v38, v50, s[44:45]
	v_cndmask_b32_e64 v10, v51, v39, s[44:45]
	v_cndmask_b32_e64 v14, v50, v38, s[44:45]
	v_lshlrev_b32_e32 v50, 16, v7
	v_mov_b32_e32 v51, v42
	v_lshlrev_b32_e32 v43, 16, v3
	v_mov_b32_e32 v52, v50
	v_pk_mul_f32 v[50:51], v[44:45], v[50:51] op_sel_hi:[0,1]
	v_pk_fma_f32 v[42:43], v[40:41], v[42:43], v[50:51] op_sel_hi:[0,1,1]
	v_pk_fma_f32 v[42:43], v[48:49], v[52:53], v[42:43] op_sel:[0,1,0] op_sel_hi:[0,0,1]
	v_cvt_pk_bf16_f32 v38, v2, v6
	v_mul_f32_e32 v2, 0xbfb8aa3b, v43
	v_exp_f32_e32 v2, v2
	v_mul_f32_e32 v6, 0xbfb8aa3b, v42
	v_exp_f32_e32 v6, v6
	v_mov_b32_e32 v54, v53
	v_mov_b32_e32 v50, v55
	v_pk_mul_f32 v[54:55], v[44:45], v[54:55] op_sel_hi:[0,1]
	v_lshlrev_b32_e32 v51, 16, v23
	v_pk_fma_f32 v[52:53], v[40:41], v[52:53], v[54:55] op_sel_hi:[0,1,1]
	v_add_f32_e32 v2, 1.0, v2
	v_pk_fma_f32 v[50:51], v[48:49], v[50:51], v[52:53] op_sel_hi:[0,1,1]
	v_rcp_f32_e32 v57, v2
	v_add_f32_e32 v2, 1.0, v6
	v_mul_f32_e32 v6, 0xbfb8aa3b, v50
	v_cvt_pk_bf16_f32 v39, v14, v10
	v_exp_f32_e32 v6, v6
	v_mul_f32_e32 v10, 0xbfb8aa3b, v51
	v_exp_f32_e32 v10, v10
	v_rcp_f32_e32 v56, v2
	v_add_f32_e32 v2, 1.0, v6
	v_rcp_f32_e32 v52, v2
	v_add_f32_e32 v2, 1.0, v10
	v_rcp_f32_e32 v53, v2
	v_and_b32_e32 v2, 0xffff0000, v11
	v_and_b32_e32 v6, 0xffff0000, v7
	v_mov_b32_e32 v7, v2
	v_mov_b32_e32 v18, v45
	v_add_u32_e32 v40, 0xd000, v0
	v_and_b32_e32 v3, 0xffff0000, v3
	v_mov_b32_e32 v10, v6
	v_mov_b32_e32 v0, v41
	v_pk_mul_f32 v[6:7], v[18:19], v[6:7] op_sel_hi:[0,1]
	v_and_b32_e32 v11, 0xffff0000, v19
	v_pk_fma_f32 v[2:3], v[0:1], v[2:3], v[6:7] op_sel_hi:[0,1,1]
	v_mov_b32_e32 v22, v49
	v_pk_fma_f32 v[2:3], v[22:23], v[10:11], v[2:3] op_sel:[0,1,0] op_sel_hi:[0,0,1]
	v_mul_f32_e32 v6, 0xbfb8aa3b, v3
	v_exp_f32_e32 v19, v6
	v_mul_f32_e32 v6, 0xbfb8aa3b, v2
	v_and_b32_e32 v7, 0xffff0000, v23
	v_exp_f32_e32 v23, v6
	v_add_f32_e32 v19, 1.0, v19
	v_rcp_f32_e32 v19, v19
	v_and_b32_e32 v15, 0xffff0000, v15
	v_mov_b32_e32 v14, v11
	v_mov_b32_e32 v6, v15
	v_pk_mul_f32 v[14:15], v[18:19], v[14:15] op_sel_hi:[0,1]
	v_add_f32_e32 v23, 1.0, v23
	v_pk_fma_f32 v[10:11], v[0:1], v[10:11], v[14:15] op_sel_hi:[0,1,1]
	v_pk_fma_f32 v[6:7], v[22:23], v[6:7], v[10:11] op_sel_hi:[0,1,1]
	v_mul_f32_e32 v0, 0xbfb8aa3b, v6
	v_exp_f32_e32 v0, v0
	v_mul_f32_e32 v10, 0xbfb8aa3b, v7
	v_exp_f32_e32 v11, v10
	v_rcp_f32_e32 v18, v23
	v_add_f32_e32 v0, 1.0, v0
	v_rcp_f32_e32 v10, v0
	v_add_f32_e32 v0, 1.0, v11
	v_rcp_f32_e32 v11, v0
	v_pk_mul_f32 v[2:3], v[2:3], v[18:19]
	v_lshlrev_b32_e32 v19, 16, v20
	v_cvt_pk_bf16_f32 v46, v60, v61
	v_pk_mul_f32 v[6:7], v[6:7], v[10:11]
	v_cvt_pk_bf16_f32 v47, v63, v62
	v_cndmask_b32_e64 v0, v7, v3, s[44:45]
	v_cndmask_b32_e64 v10, v6, v2, s[44:45]
	v_cndmask_b32_e64 v41, v2, v6, s[44:45]
	v_lshlrev_b32_e32 v6, 16, v12
	v_cvt_pk_bf16_f32 v2, v0, v10
	v_lshlrev_b32_e32 v10, 16, v8
	v_mov_b32_e32 v11, v6
	v_cndmask_b32_e64 v3, v3, v7, s[44:45]
	v_lshlrev_b32_e32 v7, 16, v4
	v_mov_b32_e32 v18, v10
	v_pk_mul_f32 v[10:11], v[30:31], v[10:11] op_sel_hi:[0,1]
	v_pk_fma_f32 v[6:7], v[26:27], v[6:7], v[10:11] op_sel_hi:[0,1,1]
	s_waitcnt vmcnt(0)
	v_pk_fma_f32 v[6:7], v[34:35], v[18:19], v[6:7] op_sel:[0,1,0] op_sel_hi:[0,0,1]
	v_mul_f32_e32 v0, 0xbfb8aa3b, v7
	v_exp_f32_e32 v0, v0
	v_mul_f32_e32 v10, 0xbfb8aa3b, v6
	v_exp_f32_e32 v10, v10
	ds_write2_b64 v40, v[46:47], v[38:39] offset1:18
	v_pk_mul_f32 v[38:39], v[42:43], v[56:57]
	v_pk_mul_f32 v[42:43], v[50:51], v[52:53]
	v_lshlrev_b32_e32 v23, 16, v16
	v_cndmask_b32_e64 v44, v43, v39, s[44:45]
	v_cndmask_b32_e64 v46, v42, v38, s[44:45]
	v_cndmask_b32_e64 v39, v39, v43, s[44:45]
	v_cndmask_b32_e64 v38, v38, v42, s[44:45]
	v_mov_b32_e32 v22, v19
	v_add_f32_e32 v0, 1.0, v0
	v_cvt_pk_bf16_f32 v15, v38, v39
	v_rcp_f32_e32 v39, v0
	v_add_f32_e32 v0, 1.0, v10
	v_mov_b32_e32 v10, v23
	v_pk_mul_f32 v[22:23], v[30:31], v[22:23] op_sel_hi:[0,1]
	v_lshlrev_b32_e32 v11, 16, v24
	v_pk_fma_f32 v[18:19], v[26:27], v[18:19], v[22:23] op_sel_hi:[0,1,1]
	v_pk_fma_f32 v[10:11], v[34:35], v[10:11], v[18:19] op_sel_hi:[0,1,1]
	v_mul_f32_e32 v18, 0xbfb8aa3b, v10
	v_exp_f32_e32 v18, v18
	v_mul_f32_e32 v19, 0xbfb8aa3b, v11
	v_exp_f32_e32 v19, v19
	v_rcp_f32_e32 v38, v0
	v_add_f32_e32 v0, 1.0, v18
	v_rcp_f32_e32 v18, v0
	v_add_f32_e32 v0, 1.0, v19
	v_rcp_f32_e32 v19, v0
	v_cvt_pk_bf16_f32 v14, v44, v46
	v_cvt_pk_bf16_f32 v3, v41, v3
	ds_write2_b64 v40, v[14:15], v[2:3] offset0:36 offset1:54
	v_pk_mul_f32 v[2:3], v[6:7], v[38:39]
	v_pk_mul_f32 v[6:7], v[10:11], v[18:19]
	v_and_b32_e32 v11, 0xffff0000, v20
	v_cndmask_b32_e64 v22, v6, v2, s[44:45]
	v_cndmask_b32_e64 v38, v2, v6, s[44:45]
	v_and_b32_e32 v2, 0xffff0000, v12
	v_cndmask_b32_e64 v0, v7, v3, s[44:45]
	v_cndmask_b32_e64 v23, v3, v7, s[44:45]
	v_and_b32_e32 v6, 0xffff0000, v8
	v_mov_b32_e32 v7, v2
	v_and_b32_e32 v3, 0xffff0000, v4
	v_mov_b32_e32 v10, v6
	v_pk_mul_f32 v[6:7], v[30:31], v[6:7] op_sel:[1,0]
	v_and_b32_e32 v15, 0xffff0000, v16
	v_pk_fma_f32 v[2:3], v[26:27], v[2:3], v[6:7] op_sel:[1,0,0]
	v_mov_b32_e32 v14, v11
	v_pk_fma_f32 v[2:3], v[34:35], v[10:11], v[2:3] op_sel:[1,1,0] op_sel_hi:[1,0,1]
	v_and_b32_e32 v7, 0xffff0000, v24
	v_mul_f32_e32 v4, 0xbfb8aa3b, v3
	v_exp_f32_e32 v4, v4
	v_mul_f32_e32 v6, 0xbfb8aa3b, v2
	v_exp_f32_e32 v8, v6
	v_mov_b32_e32 v6, v15
	v_pk_mul_f32 v[14:15], v[30:31], v[14:15] op_sel:[1,0]
	v_add_f32_e32 v4, 1.0, v4
	v_pk_fma_f32 v[10:11], v[26:27], v[10:11], v[14:15] op_sel:[1,0,0]
	v_rcp_f32_e32 v19, v4
	v_pk_fma_f32 v[6:7], v[34:35], v[6:7], v[10:11] op_sel:[1,0,0]
	v_add_f32_e32 v4, 1.0, v8
	v_mul_f32_e32 v8, 0xbfb8aa3b, v6
	v_exp_f32_e32 v8, v8
	v_mul_f32_e32 v10, 0xbfb8aa3b, v7
	v_exp_f32_e32 v11, v10
	v_rcp_f32_e32 v18, v4
	v_add_f32_e32 v4, 1.0, v8
	v_rcp_f32_e32 v10, v4
	v_add_f32_e32 v4, 1.0, v11
	v_rcp_f32_e32 v11, v4
	v_pk_mul_f32 v[2:3], v[2:3], v[18:19]
	v_cvt_pk_bf16_f32 v14, v0, v22
	v_lshlrev_b32_e32 v19, 16, v21
	v_pk_mul_f32 v[6:7], v[6:7], v[10:11]
	v_lshlrev_b32_e32 v10, 16, v9
	v_cndmask_b32_e64 v4, v6, v2, s[44:45]
	v_cndmask_b32_e64 v8, v2, v6, s[44:45]
	v_lshlrev_b32_e32 v6, 16, v13
	v_mov_b32_e32 v11, v6
	v_cndmask_b32_e64 v0, v7, v3, s[44:45]
	v_cndmask_b32_e64 v3, v3, v7, s[44:45]
	v_lshlrev_b32_e32 v7, 16, v5
	v_mov_b32_e32 v18, v10
	v_pk_mul_f32 v[10:11], v[32:33], v[10:11] op_sel_hi:[0,1]
	v_pk_fma_f32 v[6:7], v[28:29], v[6:7], v[10:11] op_sel_hi:[0,1,1]
	v_pk_fma_f32 v[6:7], v[36:37], v[18:19], v[6:7] op_sel:[0,1,0] op_sel_hi:[0,0,1]
	v_cvt_pk_bf16_f32 v2, v0, v4
	v_mul_f32_e32 v0, 0xbfb8aa3b, v7
	v_exp_f32_e32 v0, v0
	v_mul_f32_e32 v4, 0xbfb8aa3b, v6
	v_cvt_pk_bf16_f32 v15, v38, v23
	v_lshlrev_b32_e32 v23, 16, v17
	v_exp_f32_e32 v4, v4
	v_mov_b32_e32 v22, v19
	v_mov_b32_e32 v10, v23
	v_pk_mul_f32 v[22:23], v[32:33], v[22:23] op_sel_hi:[0,1]
	v_lshlrev_b32_e32 v11, 16, v25
	v_pk_fma_f32 v[18:19], v[28:29], v[18:19], v[22:23] op_sel_hi:[0,1,1]
	v_add_f32_e32 v0, 1.0, v0
	v_pk_fma_f32 v[10:11], v[36:37], v[10:11], v[18:19] op_sel_hi:[0,1,1]
	v_rcp_f32_e32 v27, v0
	v_add_f32_e32 v0, 1.0, v4
	v_mul_f32_e32 v4, 0xbfb8aa3b, v10
	v_exp_f32_e32 v4, v4
	v_mul_f32_e32 v12, 0xbfb8aa3b, v11
	v_exp_f32_e32 v12, v12
	v_rcp_f32_e32 v26, v0
	v_add_f32_e32 v0, 1.0, v4
	v_rcp_f32_e32 v18, v0
	v_add_f32_e32 v0, 1.0, v12
	v_rcp_f32_e32 v19, v0
	v_cvt_pk_bf16_f32 v3, v8, v3
	ds_write2_b64 v40, v[14:15], v[2:3] offset0:72 offset1:90
	v_pk_mul_f32 v[2:3], v[6:7], v[26:27]
	v_pk_mul_f32 v[6:7], v[10:11], v[18:19]
	v_and_b32_e32 v4, 0xffff0000, v9
	v_cndmask_b32_e64 v15, v6, v2, s[44:45]
	v_cndmask_b32_e64 v18, v2, v6, s[44:45]
	v_and_b32_e32 v2, 0xffff0000, v13
	v_cndmask_b32_e64 v14, v7, v3, s[44:45]
	v_cndmask_b32_e64 v16, v3, v7, s[44:45]
	v_and_b32_e32 v3, 0xffff0000, v5
	v_mov_b32_e32 v5, v2
	v_mov_b32_e32 v10, v33
	v_mov_b32_e32 v6, v4
	v_mov_b32_e32 v0, v29
	v_pk_mul_f32 v[4:5], v[10:11], v[4:5] op_sel_hi:[0,1]
	v_and_b32_e32 v7, 0xffff0000, v21
	v_pk_fma_f32 v[2:3], v[0:1], v[2:3], v[4:5] op_sel_hi:[0,1,1]
	v_mov_b32_e32 v12, v37
	v_pk_fma_f32 v[2:3], v[12:13], v[6:7], v[2:3] op_sel:[0,1,0] op_sel_hi:[0,0,1]
	v_mul_f32_e32 v4, 0xbfb8aa3b, v3
	v_exp_f32_e32 v11, v4
	v_mul_f32_e32 v4, 0xbfb8aa3b, v2
	v_exp_f32_e32 v13, v4
	v_and_b32_e32 v9, 0xffff0000, v17
	v_add_f32_e32 v11, 1.0, v11
	v_rcp_f32_e32 v11, v11
	v_mov_b32_e32 v8, v7
	v_mov_b32_e32 v4, v9
	v_and_b32_e32 v5, 0xffff0000, v25
	v_pk_mul_f32 v[8:9], v[10:11], v[8:9] op_sel_hi:[0,1]
	v_add_f32_e32 v13, 1.0, v13
	v_pk_fma_f32 v[6:7], v[0:1], v[6:7], v[8:9] op_sel_hi:[0,1,1]
	v_pk_fma_f32 v[4:5], v[12:13], v[4:5], v[6:7] op_sel_hi:[0,1,1]
	v_mul_f32_e32 v0, 0xbfb8aa3b, v4
	v_exp_f32_e32 v0, v0
	v_mul_f32_e32 v6, 0xbfb8aa3b, v5
	v_exp_f32_e32 v7, v6
	v_rcp_f32_e32 v10, v13
	v_add_f32_e32 v0, 1.0, v0
	v_rcp_f32_e32 v6, v0
	v_add_f32_e32 v0, 1.0, v7
	v_rcp_f32_e32 v7, v0
	v_pk_mul_f32 v[2:3], v[2:3], v[10:11]
	v_cvt_pk_bf16_f32 v8, v14, v15
	v_cvt_pk_bf16_f32 v9, v18, v16
	v_pk_mul_f32 v[4:5], v[4:5], v[6:7]
	s_nop 0
	v_cndmask_b32_e64 v0, v5, v3, s[44:45]
	v_cndmask_b32_e64 v6, v4, v2, s[44:45]
	v_cndmask_b32_e64 v3, v3, v5, s[44:45]
	v_cndmask_b32_e64 v4, v2, v4, s[44:45]
	v_cvt_pk_bf16_f32 v2, v0, v6
	v_cvt_pk_bf16_f32 v3, v4, v3
	ds_write2_b64 v40, v[8:9], v[2:3] offset0:108 offset1:126
	s_and_saveexec_b64 s[0:1], s[46:47]
	s_cbranch_execz .LBB0_598
	v_lshl_or_b32 v0, v164, 3, v163
	v_lshlrev_b32_e32 v0, 2, v0
	s_waitcnt lgkmcnt(0)
	v_mov_b32_e32 v2, s101
	s_mov_b32 s2, 0x41a00000
	s_waitcnt vmcnt(0)
	v_add_f32_e32 v2, v166, v2
	v_cmp_nlt_f32_e32 vcc, s2, v2
	s_and_saveexec_b64 s[22:23], vcc
	s_cbranch_execz .LBB0_597
	v_mul_f32_e32 v3, 0x3fb8aa3b, v2
	v_rndne_f32_e32 v4, v3
	s_mov_b32 s2, 0x3fb8aa3b
	v_sub_f32_e32 v5, v3, v4
	v_fma_f32 v3, v2, s2, -v3
	v_fmac_f32_e32 v3, 0x32a5705f, v2
	v_add_f32_e32 v3, v5, v3
	v_cvt_i32_f32_e32 v4, v4
	v_exp_f32_e32 v3, v3
	s_mov_b32 s2, 0xc2ce8ed0
	v_cmp_ngt_f32_e32 vcc, s2, v2
	s_mov_b32 s2, 0x42b17218
	v_ldexp_f32 v3, v3, v4
	v_cndmask_b32_e32 v3, 0, v3, vcc
	v_cmp_nlt_f32_e32 vcc, s2, v2
	s_mov_b32 s2, 0x3f2aaaab
	s_nop 0
	v_cndmask_b32_e32 v16, v239, v3, vcc
	v_add_f32_e32 v4, 1.0, v16
	v_add_f32_e32 v2, -1.0, v4
	v_sub_f32_e32 v3, v2, v4
	v_add_f32_e32 v3, 1.0, v3
	v_sub_f32_e32 v2, v16, v2
	v_add_f32_e32 v5, v2, v3
	v_frexp_mant_f32_e32 v6, v4
	v_cvt_f64_f32_e32 v[2:3], v4
	v_frexp_exp_i32_f64_e32 v2, v[2:3]
	v_cmp_gt_f32_e32 vcc, s2, v6
	s_mov_b32 s2, 0x3f317218
	s_nop 0
	v_subbrev_co_u32_e32 v10, vcc, 0, v2, vcc
	v_sub_u32_e32 v2, 0, v10
	v_ldexp_f32 v3, v4, v2
	v_add_f32_e32 v4, -1.0, v3
	v_add_f32_e32 v6, 1.0, v3
	v_ldexp_f32 v2, v5, v2
	v_add_f32_e32 v5, 1.0, v4
	v_add_f32_e32 v7, -1.0, v6
	v_sub_f32_e32 v5, v3, v5
	v_sub_f32_e32 v3, v3, v7
	v_add_f32_e32 v5, v2, v5
	v_add_f32_e32 v2, v2, v3
	v_add_f32_e32 v11, v6, v2
	v_rcp_f32_e32 v13, v11
	v_sub_f32_e32 v3, v6, v11
	v_add_f32_e32 v12, v2, v3
	v_add_f32_e32 v3, v4, v5
	v_mul_f32_e32 v15, v3, v13
	v_sub_f32_e32 v2, v4, v3
	v_mul_f32_e32 v4, v11, v15
	v_fma_f32 v6, v15, v11, -v4
	v_fmac_f32_e32 v6, v15, v12
	v_add_f32_e32 v14, v5, v2
	v_add_f32_e32 v2, v4, v6
	v_sub_f32_e32 v5, v3, v2
	v_pk_add_f32 v[8:9], v[2:3], v[4:5] neg_lo:[0,1] neg_hi:[0,1]
	v_mov_b32_e32 v7, v2
	v_pk_add_f32 v[2:3], v[8:9], v[6:7] neg_lo:[0,1] neg_hi:[0,1]
	s_nop 0
	v_add_f32_e32 v3, v14, v3
	v_add_f32_e32 v2, v2, v3
	v_add_f32_e32 v3, v5, v2
	v_mul_f32_e32 v14, v13, v3
	v_mul_f32_e32 v4, v11, v14
	v_fma_f32 v6, v14, v11, -v4
	v_fmac_f32_e32 v6, v14, v12
	v_sub_f32_e32 v5, v5, v3
	v_add_f32_e32 v11, v2, v5
	v_add_f32_e32 v2, v4, v6
	v_sub_f32_e32 v5, v3, v2
	v_pk_add_f32 v[8:9], v[2:3], v[4:5] neg_lo:[0,1] neg_hi:[0,1]
	v_mov_b32_e32 v7, v2
	v_pk_add_f32 v[2:3], v[8:9], v[6:7] neg_lo:[0,1] neg_hi:[0,1]
	s_nop 0
	v_add_f32_e32 v3, v11, v3
	v_add_f32_e32 v2, v2, v3
	v_add_f32_e32 v3, v15, v14
	v_add_f32_e32 v2, v5, v2
	v_sub_f32_e32 v4, v3, v15
	v_mul_f32_e32 v2, v13, v2
	v_sub_f32_e32 v4, v14, v4
	v_add_f32_e32 v4, v4, v2
	v_add_f32_e32 v6, v3, v4
	v_mul_f32_e32 v7, v6, v6
	v_fmamk_f32 v2, v7, 0x3e9b6dac, v231
	v_fmaak_f32 v203, v7, v2, 0x3f2aaada
	v_cvt_f32_i32_e32 v2, v10
	v_sub_f32_e32 v3, v6, v3
	v_sub_f32_e32 v3, v4, v3
	v_ldexp_f32 v8, v3, 1
	v_mul_f32_e32 v3, v6, v7
	v_ldexp_f32 v5, v6, 1
	v_pk_mul_f32 v[6:7], v[2:3], v[202:203]
	s_nop 0
	v_fma_f32 v4, v2, s2, -v6
	v_fmac_f32_e32 v4, 0xb102e308, v2
	v_pk_add_f32 v[2:3], v[6:7], v[4:5]
	s_mov_b32 s2, 0x7f800000
	v_sub_f32_e32 v5, v3, v5
	v_sub_f32_e32 v5, v7, v5
	v_add_f32_e32 v9, v8, v5
	v_mov_b32_e32 v8, v6
	v_pk_add_f32 v[6:7], v[2:3], v[6:7] neg_lo:[0,1] neg_hi:[0,1]
	v_pk_add_f32 v[10:11], v[2:3], v[8:9]
	v_mov_b32_e32 v5, v2
	v_mov_b32_e32 v7, v11
	v_pk_add_f32 v[12:13], v[4:5], v[6:7] neg_lo:[0,1] neg_hi:[0,1]
	v_pk_add_f32 v[4:5], v[4:5], v[6:7]
	v_mov_b32_e32 v8, v9
	v_pk_add_f32 v[6:7], v[4:5], v[2:3] op_sel:[1,0] op_sel_hi:[0,1] neg_lo:[0,1] neg_hi:[0,1]
	v_pk_add_f32 v[14:15], v[10:11], v[6:7] op_sel_hi:[1,0] neg_lo:[0,1] neg_hi:[0,1]
	v_mov_b32_e32 v10, v11
	v_mov_b32_e32 v11, v5
	v_pk_mov_b32 v[6:7], v[2:3], v[6:7] op_sel:[1,0]
	v_mov_b32_e32 v9, v2
	v_pk_add_f32 v[6:7], v[10:11], v[6:7] neg_lo:[0,1] neg_hi:[0,1]
	v_mov_b32_e32 v14, v12
	v_pk_add_f32 v[2:3], v[8:9], v[6:7] neg_lo:[0,1] neg_hi:[0,1]
	v_mov_b32_e32 v13, v5
	v_pk_add_f32 v[6:7], v[14:15], v[2:3]
	v_cmp_neq_f32_e32 vcc, s2, v16
	v_pk_add_f32 v[8:9], v[6:7], v[6:7] op_sel:[0,1] op_sel_hi:[1,0]
	s_mov_b32 s2, 0x33800000
	v_pk_add_f32 v[4:5], v[4:5], v[8:9] op_sel:[1,0] op_sel_hi:[0,1]
	v_mov_b32_e32 v7, v4
	v_pk_add_f32 v[10:11], v[6:7], v[12:13] neg_lo:[0,1] neg_hi:[0,1]
	v_mov_b32_e32 v3, v8
	v_sub_f32_e32 v5, v6, v10
	v_pk_add_f32 v[2:3], v[2:3], v[10:11] neg_lo:[0,1] neg_hi:[0,1]
	v_sub_f32_e32 v5, v12, v5
	v_add_f32_e32 v2, v2, v5
	v_add_f32_e32 v2, v2, v3
	v_add_f32_e32 v2, v4, v2
	v_cndmask_b32_e32 v2, v239, v2, vcc
	v_cmp_lt_f32_e64 vcc, |v16|, s2
	s_nop 1
	v_cndmask_b32_e32 v2, v2, v16, vcc

	.amdhsa_kernel _Z14fwd_megakernel6Params
		.amdhsa_group_segment_fixed_size 0
		.amdhsa_private_segment_fixed_size 0
		.amdhsa_kernarg_size 416
		.amdhsa_user_sgpr_count 2
		.amdhsa_user_sgpr_dispatch_ptr 0
		.amdhsa_user_sgpr_queue_ptr 0
		.amdhsa_user_sgpr_kernarg_segment_ptr 1
		.amdhsa_user_sgpr_dispatch_id 0
		.amdhsa_user_sgpr_kernarg_preload_length 0
		.amdhsa_user_sgpr_kernarg_preload_offset 0
		.amdhsa_user_sgpr_private_segment_size 0
		.amdhsa_uses_dynamic_stack 0
		.amdhsa_enable_private_segment 0
		.amdhsa_system_sgpr_workgroup_id_x 1
		.amdhsa_system_sgpr_workgroup_id_y 0
		.amdhsa_system_sgpr_workgroup_id_z 0
		.amdhsa_system_sgpr_workgroup_info 0
		.amdhsa_system_vgpr_workitem_id 2
		.amdhsa_next_free_vgpr 256
		.amdhsa_next_free_sgpr 102
		.amdhsa_accum_offset 256
		.amdhsa_reserve_vcc 1
		.amdhsa_float_round_mode_32 0
		.amdhsa_float_round_mode_16_64 0
		.amdhsa_float_denorm_mode_32 3
		.amdhsa_float_denorm_mode_16_64 3
		.amdhsa_dx10_clamp 1
		.amdhsa_ieee_mode 1
		.amdhsa_fp16_overflow 0
		.amdhsa_tg_split 0
		.amdhsa_exception_fp_ieee_invalid_op 0
		.amdhsa_exception_fp_denorm_src 0
		.amdhsa_exception_fp_ieee_div_zero 0
		.amdhsa_exception_fp_ieee_overflow 0
		.amdhsa_exception_fp_ieee_underflow 0
		.amdhsa_exception_fp_ieee_inexact 0
		.amdhsa_exception_int_div_zero 0
	.end_amdhsa_kernel

amdhsa.kernels:
  - .agpr_count:     0
    .args:
      - .offset:         0
        .size:           160
        .value_kind:     by_value
      - .offset:         160
        .size:           4
        .value_kind:     hidden_block_count_x
      - .offset:         164
        .size:           4
        .value_kind:     hidden_block_count_y
      - .offset:         168
        .size:           4
        .value_kind:     hidden_block_count_z
      - .offset:         172
        .size:           2
        .value_kind:     hidden_group_size_x
      - .offset:         174
        .size:           2
        .value_kind:     hidden_group_size_y
      - .offset:         176
        .size:           2
        .value_kind:     hidden_group_size_z
      - .offset:         178
        .size:           2
        .value_kind:     hidden_remainder_x
      - .offset:         180
        .size:           2
        .value_kind:     hidden_remainder_y
      - .offset:         182
        .size:           2
        .value_kind:     hidden_remainder_z
      - .offset:         200
        .size:           8
        .value_kind:     hidden_global_offset_x
      - .offset:         208
        .size:           8
        .value_kind:     hidden_global_offset_y
      - .offset:         216
        .size:           8
        .value_kind:     hidden_global_offset_z
      - .offset:         224
        .size:           2
        .value_kind:     hidden_grid_dims
      - .offset:         248
        .size:           8
        .value_kind:     hidden_multigrid_sync_arg
      - .offset:         280
        .size:           4
        .value_kind:     hidden_dynamic_lds_size
    .group_segment_fixed_size: 0
    .kernarg_segment_align: 8
    .kernarg_segment_size: 416
    .language:       OpenCL C
    .language_version:
      - 2
      - 0
    .max_flat_workgroup_size: 512
    .name:           _Z14fwd_megakernel6Params
    .private_segment_fixed_size: 0
    .sgpr_count:     108
    .sgpr_spill_count: 368
    .symbol:         _Z14fwd_megakernel6Params.kd
    .uniform_work_group_size: 1
    .uses_dynamic_stack: false
    .vgpr_count:     256
    .vgpr_spill_count: 0
    .wavefront_size: 64
